# norm prefetch overlap waits + last-unit write-through epilogues (out/ff1/ff2) + no setprio in GEMM K-loops
# speedup vs baseline: 1.0056x; 1.0056x over previous
.LBB0_565:
	s_add_u32 s8, s6, 0xfff80080
	s_addc_u32 s9, s7, -1
	s_add_i32 s56, 0, 0x10000
	s_cmp_eq_u32 s51, 28
	s_cselect_b32 s11, s28, s9
	s_cselect_b32 s10, s34, s8
	v_add_u32_e32 v2, s56, v193
	s_cselect_b32 s9, s35, s49
	s_cselect_b32 s8, s44, s45
	s_add_i32 s58, 0, 0x14000
	ds_read_b128 v[132:135], v2
	ds_read_b128 v[136:139], v2 offset:1024
	ds_read_b128 v[140:143], v2 offset:2048
	ds_read_b128 v[144:147], v2 offset:3072
	v_add_u32_e32 v2, s58, v193
	ds_read_b128 v[148:151], v2
	ds_read_b128 v[152:155], v2 offset:1024
	ds_read_b128 v[156:159], v2 offset:2048
	ds_read_b128 v[160:163], v2 offset:3072
	v_lshl_add_u64 v[236:237], s[6:7], 0, v[188:189]
	s_add_i32 m0, s16, 0xc000
	ds_read_b128 v[164:167], v207
	ds_read_b128 v[208:211], v207 offset:1024
	ds_read_b128 v[212:215], v207 offset:2048
	ds_read_b128 v[216:219], v207 offset:3072
	ds_read_b128 v[220:223], v207 offset:4096
	ds_read_b128 v[224:227], v207 offset:5120
	ds_read_b128 v[228:231], v207 offset:6144
	ds_read_b128 v[232:235], v207 offset:7168
	global_load_lds_dwordx4 v[236:237], off
	v_lshl_add_u64 v[236:237], s[6:7], 0, v[190:191]
	s_add_i32 m0, s16, 0xe000
	s_nop 0
	global_load_lds_dwordx4 v[236:237], off
	s_waitcnt vmcnt(8)
	s_waitcnt lgkmcnt(0)
	s_barrier
	s_waitcnt lgkmcnt(0)
	v_mfma_f32_16x16x32_bf16 v[128:131], v[132:135], v[164:167], v[128:131]
	v_mfma_f32_16x16x32_bf16 v[124:127], v[140:143], v[164:167], v[124:127]
	v_mfma_f32_16x16x32_bf16 v[112:115], v[132:135], v[212:215], v[112:115]
	v_mfma_f32_16x16x32_bf16 v[108:111], v[140:143], v[212:215], v[108:111]
	v_mfma_f32_16x16x32_bf16 v[96:99], v[132:135], v[220:223], v[96:99]
	v_mfma_f32_16x16x32_bf16 v[92:95], v[140:143], v[220:223], v[92:95]
	v_mfma_f32_16x16x32_bf16 v[80:83], v[132:135], v[228:231], v[80:83]
	v_mfma_f32_16x16x32_bf16 v[76:79], v[140:143], v[228:231], v[76:79]
	v_mfma_f32_16x16x32_bf16 v[128:131], v[136:139], v[208:211], v[128:131]
	v_mfma_f32_16x16x32_bf16 v[124:127], v[144:147], v[208:211], v[124:127]
	v_mfma_f32_16x16x32_bf16 v[112:115], v[136:139], v[216:219], v[112:115]
	v_mfma_f32_16x16x32_bf16 v[108:111], v[144:147], v[216:219], v[108:111]
	v_mfma_f32_16x16x32_bf16 v[96:99], v[136:139], v[224:227], v[96:99]
	v_mfma_f32_16x16x32_bf16 v[92:95], v[144:147], v[224:227], v[92:95]
	v_mfma_f32_16x16x32_bf16 v[80:83], v[136:139], v[232:235], v[80:83]
	v_mfma_f32_16x16x32_bf16 v[76:79], v[144:147], v[232:235], v[76:79]
	v_mfma_f32_16x16x32_bf16 v[120:123], v[148:151], v[164:167], v[120:123]
	v_mfma_f32_16x16x32_bf16 v[116:119], v[156:159], v[164:167], v[116:119]
	v_mfma_f32_16x16x32_bf16 v[104:107], v[148:151], v[212:215], v[104:107]
	v_mfma_f32_16x16x32_bf16 v[100:103], v[156:159], v[212:215], v[100:103]
	v_mfma_f32_16x16x32_bf16 v[88:91], v[148:151], v[220:223], v[88:91]
	v_mfma_f32_16x16x32_bf16 v[84:87], v[156:159], v[220:223], v[84:87]
	v_mfma_f32_16x16x32_bf16 v[72:75], v[148:151], v[228:231], v[72:75]
	v_mfma_f32_16x16x32_bf16 v[68:71], v[156:159], v[228:231], v[68:71]
	v_mfma_f32_16x16x32_bf16 v[120:123], v[152:155], v[208:211], v[120:123]
	v_mfma_f32_16x16x32_bf16 v[116:119], v[160:163], v[208:211], v[116:119]
	v_mfma_f32_16x16x32_bf16 v[104:107], v[152:155], v[216:219], v[104:107]
	v_mfma_f32_16x16x32_bf16 v[100:103], v[160:163], v[216:219], v[100:103]
	v_mfma_f32_16x16x32_bf16 v[88:91], v[152:155], v[224:227], v[88:91]
	v_mfma_f32_16x16x32_bf16 v[84:87], v[160:163], v[224:227], v[84:87]
	v_mfma_f32_16x16x32_bf16 v[72:75], v[152:155], v[232:235], v[72:75]
	v_mfma_f32_16x16x32_bf16 v[68:71], v[160:163], v[232:235], v[68:71]
	s_barrier
	s_add_i32 s56, s56, s15
	v_lshl_add_u64 v[236:237], s[8:9], 0, v[184:185]
	s_mov_b32 m0, s56
	ds_read_b128 v[164:167], v207 offset:16384
	ds_read_b128 v[208:211], v207 offset:17408
	ds_read_b128 v[212:215], v207 offset:18432
	ds_read_b128 v[216:219], v207 offset:19456
	ds_read_b128 v[220:223], v207 offset:20480
	ds_read_b128 v[224:227], v207 offset:21504
	ds_read_b128 v[228:231], v207 offset:22528
	ds_read_b128 v[232:235], v207 offset:23552
	global_load_lds_dwordx4 v[236:237], off
	s_add_i32 m0, s56, 0x2000
	s_add_u32 s56, s8, 0x80000
	v_lshl_add_u64 v[238:239], s[8:9], 0, v[180:181]
	s_addc_u32 s57, s9, 0
	s_add_i32 s58, s58, s15
	global_load_lds_dwordx4 v[238:239], off
	v_lshl_add_u64 v[240:241], s[56:57], 0, v[184:185]
	s_mov_b32 m0, s58
	v_lshl_add_u64 v[242:243], s[10:11], 0, v[182:183]
	global_load_lds_dwordx4 v[240:241], off
	v_lshl_add_u64 v[240:241], s[56:57], 0, v[180:181]
	s_add_i32 m0, s58, 0x2000
	s_nop 0
	global_load_lds_dwordx4 v[240:241], off
	v_lshl_add_u64 v[240:241], s[10:11], 0, v[186:187]
	s_mov_b32 m0, s16
	s_nop 0
	global_load_lds_dwordx4 v[240:241], off
	s_mov_b32 m0, s17
	s_nop 0
	global_load_lds_dwordx4 v[242:243], off
	s_waitcnt vmcnt(8)
	s_waitcnt lgkmcnt(0)
	s_barrier
	s_waitcnt lgkmcnt(0)
	v_mfma_f32_16x16x32_bf16 v[64:67], v[132:135], v[164:167], v[64:67]
	v_mfma_f32_16x16x32_bf16 v[60:63], v[140:143], v[164:167], v[60:63]
	v_mfma_f32_16x16x32_bf16 v[48:51], v[132:135], v[212:215], v[48:51]
	v_mfma_f32_16x16x32_bf16 v[44:47], v[140:143], v[212:215], v[44:47]
	v_mfma_f32_16x16x32_bf16 v[32:35], v[132:135], v[220:223], v[32:35]
	v_mfma_f32_16x16x32_bf16 v[28:31], v[140:143], v[220:223], v[28:31]
	v_mfma_f32_16x16x32_bf16 v[16:19], v[132:135], v[228:231], v[16:19]
	v_mfma_f32_16x16x32_bf16 v[12:15], v[140:143], v[228:231], v[12:15]
	v_mfma_f32_16x16x32_bf16 v[64:67], v[136:139], v[208:211], v[64:67]
	v_mfma_f32_16x16x32_bf16 v[60:63], v[144:147], v[208:211], v[60:63]
	v_mfma_f32_16x16x32_bf16 v[48:51], v[136:139], v[216:219], v[48:51]
	v_mfma_f32_16x16x32_bf16 v[44:47], v[144:147], v[216:219], v[44:47]
	v_mfma_f32_16x16x32_bf16 v[32:35], v[136:139], v[224:227], v[32:35]
	v_mfma_f32_16x16x32_bf16 v[28:31], v[144:147], v[224:227], v[28:31]
	v_mfma_f32_16x16x32_bf16 v[16:19], v[136:139], v[232:235], v[16:19]
	v_mfma_f32_16x16x32_bf16 v[12:15], v[144:147], v[232:235], v[12:15]
	v_mfma_f32_16x16x32_bf16 v[56:59], v[148:151], v[164:167], v[56:59]
	v_mfma_f32_16x16x32_bf16 v[52:55], v[156:159], v[164:167], v[52:55]
	v_mfma_f32_16x16x32_bf16 v[40:43], v[148:151], v[212:215], v[40:43]
	v_mfma_f32_16x16x32_bf16 v[36:39], v[156:159], v[212:215], v[36:39]
	v_mfma_f32_16x16x32_bf16 v[24:27], v[148:151], v[220:223], v[24:27]
	v_mfma_f32_16x16x32_bf16 v[20:23], v[156:159], v[220:223], v[20:23]
	v_mfma_f32_16x16x32_bf16 v[8:11], v[148:151], v[228:231], v[8:11]
	v_mfma_f32_16x16x32_bf16 v[4:7], v[156:159], v[228:231], v[4:7]
	v_mfma_f32_16x16x32_bf16 v[56:59], v[152:155], v[208:211], v[56:59]
	v_mfma_f32_16x16x32_bf16 v[52:55], v[160:163], v[208:211], v[52:55]
	v_mfma_f32_16x16x32_bf16 v[40:43], v[152:155], v[216:219], v[40:43]
	v_mfma_f32_16x16x32_bf16 v[36:39], v[160:163], v[216:219], v[36:39]
	v_mfma_f32_16x16x32_bf16 v[24:27], v[152:155], v[224:227], v[24:27]
	v_mfma_f32_16x16x32_bf16 v[20:23], v[160:163], v[224:227], v[20:23]
	v_mfma_f32_16x16x32_bf16 v[8:11], v[152:155], v[232:235], v[8:11]
	v_mfma_f32_16x16x32_bf16 v[4:7], v[160:163], v[232:235], v[4:7]
	s_barrier
	s_add_i32 s56, 0, 0x18000
	v_add_u32_e32 v2, s56, v193
	s_add_i32 s57, 0, 0x1c000
	ds_read_b128 v[132:135], v2
	ds_read_b128 v[136:139], v2 offset:1024
	ds_read_b128 v[140:143], v2 offset:2048
	ds_read_b128 v[144:147], v2 offset:3072
	v_add_u32_e32 v2, s57, v193
	ds_read_b128 v[148:151], v2
	ds_read_b128 v[152:155], v2 offset:1024
	ds_read_b128 v[156:159], v2 offset:2048
	ds_read_b128 v[160:163], v2 offset:3072
	s_add_u32 s10, s10, 0x80000
	s_addc_u32 s11, s11, 0
	s_mov_b32 m0, s18
	v_lshl_add_u64 v[244:245], s[10:11], 0, v[186:187]
	ds_read_b128 v[164:167], v207 offset:32768
	ds_read_b128 v[208:211], v207 offset:33792
	ds_read_b128 v[212:215], v207 offset:34816
	ds_read_b128 v[216:219], v207 offset:35840
	ds_read_b128 v[220:223], v207 offset:36864
	ds_read_b128 v[224:227], v207 offset:37888
	ds_read_b128 v[228:231], v207 offset:38912
	ds_read_b128 v[232:235], v207 offset:39936
	global_load_lds_dwordx4 v[244:245], off
	v_lshl_add_u64 v[244:245], s[10:11], 0, v[182:183]
	s_mov_b32 m0, s19
	s_nop 0
	global_load_lds_dwordx4 v[244:245], off
	s_waitcnt vmcnt(8)
	s_waitcnt lgkmcnt(0)
	s_barrier
	s_waitcnt lgkmcnt(0)
	v_mfma_f32_16x16x32_bf16 v[128:131], v[132:135], v[164:167], v[128:131]
	v_mfma_f32_16x16x32_bf16 v[124:127], v[140:143], v[164:167], v[124:127]
	v_mfma_f32_16x16x32_bf16 v[112:115], v[132:135], v[212:215], v[112:115]
	v_mfma_f32_16x16x32_bf16 v[108:111], v[140:143], v[212:215], v[108:111]
	v_mfma_f32_16x16x32_bf16 v[96:99], v[132:135], v[220:223], v[96:99]
	v_mfma_f32_16x16x32_bf16 v[92:95], v[140:143], v[220:223], v[92:95]
	v_mfma_f32_16x16x32_bf16 v[80:83], v[132:135], v[228:231], v[80:83]
	v_mfma_f32_16x16x32_bf16 v[76:79], v[140:143], v[228:231], v[76:79]
	v_mfma_f32_16x16x32_bf16 v[128:131], v[136:139], v[208:211], v[128:131]
	v_mfma_f32_16x16x32_bf16 v[124:127], v[144:147], v[208:211], v[124:127]
	v_mfma_f32_16x16x32_bf16 v[112:115], v[136:139], v[216:219], v[112:115]
	v_mfma_f32_16x16x32_bf16 v[108:111], v[144:147], v[216:219], v[108:111]
	v_mfma_f32_16x16x32_bf16 v[96:99], v[136:139], v[224:227], v[96:99]
	v_mfma_f32_16x16x32_bf16 v[92:95], v[144:147], v[224:227], v[92:95]
	v_mfma_f32_16x16x32_bf16 v[80:83], v[136:139], v[232:235], v[80:83]
	v_mfma_f32_16x16x32_bf16 v[76:79], v[144:147], v[232:235], v[76:79]
	v_mfma_f32_16x16x32_bf16 v[120:123], v[148:151], v[164:167], v[120:123]
	v_mfma_f32_16x16x32_bf16 v[116:119], v[156:159], v[164:167], v[116:119]
	v_mfma_f32_16x16x32_bf16 v[104:107], v[148:151], v[212:215], v[104:107]
	v_mfma_f32_16x16x32_bf16 v[100:103], v[156:159], v[212:215], v[100:103]
	v_mfma_f32_16x16x32_bf16 v[88:91], v[148:151], v[220:223], v[88:91]
	v_mfma_f32_16x16x32_bf16 v[84:87], v[156:159], v[220:223], v[84:87]
	v_mfma_f32_16x16x32_bf16 v[72:75], v[148:151], v[228:231], v[72:75]
	v_mfma_f32_16x16x32_bf16 v[68:71], v[156:159], v[228:231], v[68:71]
	v_mfma_f32_16x16x32_bf16 v[120:123], v[152:155], v[208:211], v[120:123]
	v_mfma_f32_16x16x32_bf16 v[116:119], v[160:163], v[208:211], v[116:119]
	v_mfma_f32_16x16x32_bf16 v[104:107], v[152:155], v[216:219], v[104:107]
	v_mfma_f32_16x16x32_bf16 v[100:103], v[160:163], v[216:219], v[100:103]
	v_mfma_f32_16x16x32_bf16 v[88:91], v[152:155], v[224:227], v[88:91]
	v_mfma_f32_16x16x32_bf16 v[84:87], v[160:163], v[224:227], v[84:87]
	v_mfma_f32_16x16x32_bf16 v[72:75], v[152:155], v[232:235], v[72:75]
	v_mfma_f32_16x16x32_bf16 v[68:71], v[160:163], v[232:235], v[68:71]
	s_barrier
	s_add_i32 s10, s56, s15
	v_lshl_add_u64 v[236:237], v[236:237], 0, s[2:3]
	s_mov_b32 m0, s10
	ds_read_b128 v[164:167], v207 offset:49152
	ds_read_b128 v[208:211], v207 offset:50176
	ds_read_b128 v[212:215], v207 offset:51200
	ds_read_b128 v[216:219], v207 offset:52224
	ds_read_b128 v[220:223], v207 offset:53248
	ds_read_b128 v[224:227], v207 offset:54272
	ds_read_b128 v[228:231], v207 offset:55296
	ds_read_b128 v[232:235], v207 offset:56320
	global_load_lds_dwordx4 v[236:237], off
	s_add_i32 m0, s10, 0x2000
	s_add_u32 s8, s8, 0x80080
	v_lshl_add_u64 v[236:237], v[238:239], 0, s[2:3]
	s_addc_u32 s9, s9, 0
	s_add_i32 s10, s57, s15
	global_load_lds_dwordx4 v[236:237], off
	v_lshl_add_u64 v[236:237], s[8:9], 0, v[184:185]
	s_mov_b32 m0, s10
	s_nop 0
	global_load_lds_dwordx4 v[236:237], off
	v_lshl_add_u64 v[236:237], s[8:9], 0, v[180:181]
	s_add_i32 m0, s10, 0x2000
	s_nop 0
	global_load_lds_dwordx4 v[236:237], off
	v_lshl_add_u64 v[236:237], v[240:241], 0, s[2:3]
	s_mov_b32 m0, s20
	s_nop 0
	global_load_lds_dwordx4 v[236:237], off
	v_lshl_add_u64 v[236:237], v[242:243], 0, s[2:3]
	s_mov_b32 m0, s21
	s_nop 0
	global_load_lds_dwordx4 v[236:237], off
	s_waitcnt vmcnt(8)
	s_waitcnt lgkmcnt(0)
	s_barrier
	s_waitcnt lgkmcnt(0)
	v_mfma_f32_16x16x32_bf16 v[64:67], v[132:135], v[164:167], v[64:67]
	v_mfma_f32_16x16x32_bf16 v[60:63], v[140:143], v[164:167], v[60:63]
	v_mfma_f32_16x16x32_bf16 v[48:51], v[132:135], v[212:215], v[48:51]
	v_mfma_f32_16x16x32_bf16 v[44:47], v[140:143], v[212:215], v[44:47]
	v_mfma_f32_16x16x32_bf16 v[32:35], v[132:135], v[220:223], v[32:35]
	v_mfma_f32_16x16x32_bf16 v[28:31], v[140:143], v[220:223], v[28:31]
	v_mfma_f32_16x16x32_bf16 v[16:19], v[132:135], v[228:231], v[16:19]
	v_mfma_f32_16x16x32_bf16 v[12:15], v[140:143], v[228:231], v[12:15]
	v_mfma_f32_16x16x32_bf16 v[64:67], v[136:139], v[208:211], v[64:67]
	v_mfma_f32_16x16x32_bf16 v[60:63], v[144:147], v[208:211], v[60:63]
	v_mfma_f32_16x16x32_bf16 v[48:51], v[136:139], v[216:219], v[48:51]
	v_mfma_f32_16x16x32_bf16 v[44:47], v[144:147], v[216:219], v[44:47]
	v_mfma_f32_16x16x32_bf16 v[32:35], v[136:139], v[224:227], v[32:35]
	v_mfma_f32_16x16x32_bf16 v[28:31], v[144:147], v[224:227], v[28:31]
	v_mfma_f32_16x16x32_bf16 v[16:19], v[136:139], v[232:235], v[16:19]
	v_mfma_f32_16x16x32_bf16 v[12:15], v[144:147], v[232:235], v[12:15]
	v_mfma_f32_16x16x32_bf16 v[56:59], v[148:151], v[164:167], v[56:59]
	v_mfma_f32_16x16x32_bf16 v[52:55], v[156:159], v[164:167], v[52:55]
	v_mfma_f32_16x16x32_bf16 v[40:43], v[148:151], v[212:215], v[40:43]
	v_mfma_f32_16x16x32_bf16 v[36:39], v[156:159], v[212:215], v[36:39]
	v_mfma_f32_16x16x32_bf16 v[24:27], v[148:151], v[220:223], v[24:27]
	v_mfma_f32_16x16x32_bf16 v[20:23], v[156:159], v[220:223], v[20:23]
	v_mfma_f32_16x16x32_bf16 v[8:11], v[148:151], v[228:231], v[8:11]
	v_mfma_f32_16x16x32_bf16 v[4:7], v[156:159], v[228:231], v[4:7]
	v_mfma_f32_16x16x32_bf16 v[56:59], v[152:155], v[208:211], v[56:59]
	v_mfma_f32_16x16x32_bf16 v[52:55], v[160:163], v[208:211], v[52:55]
	v_mfma_f32_16x16x32_bf16 v[40:43], v[152:155], v[216:219], v[40:43]
	v_mfma_f32_16x16x32_bf16 v[36:39], v[160:163], v[216:219], v[36:39]
	v_mfma_f32_16x16x32_bf16 v[24:27], v[152:155], v[224:227], v[24:27]
	v_mfma_f32_16x16x32_bf16 v[20:23], v[160:163], v[224:227], v[20:23]
	v_mfma_f32_16x16x32_bf16 v[8:11], v[152:155], v[232:235], v[8:11]
	v_mfma_f32_16x16x32_bf16 v[4:7], v[160:163], v[232:235], v[4:7]
	s_barrier
	s_add_i32 s51, s51, 2
	s_add_u32 s6, s6, 0x100
	s_addc_u32 s7, s7, 0
	s_add_u32 s45, s45, 0x100
	s_addc_u32 s49, s49, 0
	s_cmp_gt_u32 s51, 29
	s_cbranch_scc0 .LBB0_565
	s_and_b64 vcc, exec, s[46:47]
	s_cbranch_vccz .LBB0_568
	s_barrier

.LBB0_1012:
	s_add_u32 s20, s16, s18
	s_addc_u32 s21, s17, s19
	s_add_u32 s20, s20, 0x100
	s_addc_u32 s21, s21, 0
	s_add_u32 s48, s45, s18
	s_addc_u32 s49, s46, s19
	s_add_i32 s50, 0, 0x10000
	s_cmpk_eq_i32 s18, 0xf00
	s_cselect_b32 s25, s11, s21
	s_cselect_b32 s24, s43, s20
	v_add_u32_e32 v2, s50, v1
	s_cselect_b32 s21, s9, s49
	s_cselect_b32 s20, s44, s48
	s_add_i32 s51, 0, 0x14000
	ds_read_b128 v[134:137], v2
	ds_read_b128 v[138:141], v2 offset:1024
	ds_read_b128 v[142:145], v2 offset:2048
	ds_read_b128 v[180:183], v2 offset:3072
	v_add_u32_e32 v2, s51, v1
	ds_read_b128 v[184:187], v2
	ds_read_b128 v[188:191], v2 offset:1024
	ds_read_b128 v[192:195], v2 offset:2048
	ds_read_b128 v[196:199], v2 offset:3072
	v_lshl_add_u64 v[4:5], v[158:159], 0, s[18:19]
	s_add_i32 m0, s34, 0xc000
	ds_read_b128 v[208:211], v163
	ds_read_b128 v[212:215], v163 offset:1024
	ds_read_b128 v[216:219], v163 offset:2048
	ds_read_b128 v[220:223], v163 offset:3072
	ds_read_b128 v[224:227], v163 offset:4096
	ds_read_b128 v[228:231], v163 offset:5120
	ds_read_b128 v[232:235], v163 offset:6144
	ds_read_b128 v[236:239], v163 offset:7168
	global_load_lds_dwordx4 v[4:5], off
	v_lshl_add_u64 v[4:5], v[160:161], 0, s[18:19]
	s_add_i32 m0, s34, 0xe000
	s_nop 0
	global_load_lds_dwordx4 v[4:5], off
	s_waitcnt vmcnt(8)
	s_waitcnt lgkmcnt(0)
	s_barrier
	s_waitcnt lgkmcnt(0)
	v_mfma_f32_16x16x32_bf16 v[130:133], v[134:137], v[208:211], v[130:133]
	v_mfma_f32_16x16x32_bf16 v[126:129], v[142:145], v[208:211], v[126:129]
	v_mfma_f32_16x16x32_bf16 v[118:121], v[134:137], v[216:219], v[118:121]
	v_mfma_f32_16x16x32_bf16 v[110:113], v[142:145], v[216:219], v[110:113]
	v_mfma_f32_16x16x32_bf16 v[98:101], v[134:137], v[224:227], v[98:101]
	v_mfma_f32_16x16x32_bf16 v[94:97], v[142:145], v[224:227], v[94:97]
	v_mfma_f32_16x16x32_bf16 v[82:85], v[134:137], v[232:235], v[82:85]
	v_mfma_f32_16x16x32_bf16 v[78:81], v[142:145], v[232:235], v[78:81]
	v_mfma_f32_16x16x32_bf16 v[130:133], v[138:141], v[212:215], v[130:133]
	v_mfma_f32_16x16x32_bf16 v[126:129], v[180:183], v[212:215], v[126:129]
	v_mfma_f32_16x16x32_bf16 v[118:121], v[138:141], v[220:223], v[118:121]
	v_mfma_f32_16x16x32_bf16 v[110:113], v[180:183], v[220:223], v[110:113]
	v_mfma_f32_16x16x32_bf16 v[98:101], v[138:141], v[228:231], v[98:101]
	v_mfma_f32_16x16x32_bf16 v[94:97], v[180:183], v[228:231], v[94:97]
	v_mfma_f32_16x16x32_bf16 v[82:85], v[138:141], v[236:239], v[82:85]
	v_mfma_f32_16x16x32_bf16 v[78:81], v[180:183], v[236:239], v[78:81]
	v_mfma_f32_16x16x32_bf16 v[122:125], v[184:187], v[208:211], v[122:125]
	v_mfma_f32_16x16x32_bf16 v[114:117], v[192:195], v[208:211], v[114:117]
	v_mfma_f32_16x16x32_bf16 v[106:109], v[184:187], v[216:219], v[106:109]
	v_mfma_f32_16x16x32_bf16 v[102:105], v[192:195], v[216:219], v[102:105]
	v_mfma_f32_16x16x32_bf16 v[90:93], v[184:187], v[224:227], v[90:93]
	v_mfma_f32_16x16x32_bf16 v[86:89], v[192:195], v[224:227], v[86:89]
	v_mfma_f32_16x16x32_bf16 v[74:77], v[184:187], v[232:235], v[74:77]
	v_mfma_f32_16x16x32_bf16 v[70:73], v[192:195], v[232:235], v[70:73]
	v_mfma_f32_16x16x32_bf16 v[122:125], v[188:191], v[212:215], v[122:125]
	v_mfma_f32_16x16x32_bf16 v[114:117], v[196:199], v[212:215], v[114:117]
	v_mfma_f32_16x16x32_bf16 v[106:109], v[188:191], v[220:223], v[106:109]
	v_mfma_f32_16x16x32_bf16 v[102:105], v[196:199], v[220:223], v[102:105]
	v_mfma_f32_16x16x32_bf16 v[90:93], v[188:191], v[228:231], v[90:93]
	v_mfma_f32_16x16x32_bf16 v[86:89], v[196:199], v[228:231], v[86:89]
	v_mfma_f32_16x16x32_bf16 v[74:77], v[188:191], v[236:239], v[74:77]
	v_mfma_f32_16x16x32_bf16 v[70:73], v[196:199], v[236:239], v[70:73]
	s_barrier
	s_add_i32 s48, s50, s28
	v_lshl_add_u64 v[166:167], s[20:21], 0, v[150:151]
	s_mov_b32 m0, s48
	ds_read_b128 v[208:211], v163 offset:16384
	ds_read_b128 v[212:215], v163 offset:17408
	ds_read_b128 v[216:219], v163 offset:18432
	ds_read_b128 v[220:223], v163 offset:19456
	ds_read_b128 v[224:227], v163 offset:20480
	ds_read_b128 v[228:231], v163 offset:21504
	ds_read_b128 v[232:235], v163 offset:22528
	ds_read_b128 v[236:239], v163 offset:23552
	global_load_lds_dwordx4 v[166:167], off
	s_add_i32 m0, s48, 0x2000
	s_add_u32 s48, s20, 0x80000
	v_lshl_add_u64 v[240:241], s[20:21], 0, v[146:147]
	s_addc_u32 s49, s21, 0
	s_add_i32 s50, s51, s28
	global_load_lds_dwordx4 v[240:241], off
	v_lshl_add_u64 v[4:5], s[48:49], 0, v[150:151]
	s_mov_b32 m0, s50
	v_lshl_add_u64 v[242:243], s[24:25], 0, v[152:153]
	global_load_lds_dwordx4 v[4:5], off
	v_lshl_add_u64 v[4:5], s[48:49], 0, v[146:147]
	s_add_i32 m0, s50, 0x2000
	v_lshl_add_u64 v[244:245], s[24:25], 0, v[148:149]
	global_load_lds_dwordx4 v[4:5], off
	s_mov_b32 m0, s34
	s_nop 0
	global_load_lds_dwordx4 v[242:243], off
	s_mov_b32 m0, s35
	s_nop 0
	global_load_lds_dwordx4 v[244:245], off
	s_waitcnt vmcnt(8)
	s_waitcnt lgkmcnt(0)
	s_barrier
	s_waitcnt lgkmcnt(0)
	v_mfma_f32_16x16x32_bf16 v[66:69], v[134:137], v[208:211], v[66:69]
	v_mfma_f32_16x16x32_bf16 v[62:65], v[142:145], v[208:211], v[62:65]
	v_mfma_f32_16x16x32_bf16 v[50:53], v[134:137], v[216:219], v[50:53]
	v_mfma_f32_16x16x32_bf16 v[46:49], v[142:145], v[216:219], v[46:49]
	v_mfma_f32_16x16x32_bf16 v[34:37], v[134:137], v[224:227], v[34:37]
	v_mfma_f32_16x16x32_bf16 v[30:33], v[142:145], v[224:227], v[30:33]
	v_mfma_f32_16x16x32_bf16 v[18:21], v[134:137], v[232:235], v[18:21]
	v_mfma_f32_16x16x32_bf16 v[14:17], v[142:145], v[232:235], v[14:17]
	v_mfma_f32_16x16x32_bf16 v[66:69], v[138:141], v[212:215], v[66:69]
	v_mfma_f32_16x16x32_bf16 v[62:65], v[180:183], v[212:215], v[62:65]
	v_mfma_f32_16x16x32_bf16 v[50:53], v[138:141], v[220:223], v[50:53]
	v_mfma_f32_16x16x32_bf16 v[46:49], v[180:183], v[220:223], v[46:49]
	v_mfma_f32_16x16x32_bf16 v[34:37], v[138:141], v[228:231], v[34:37]
	v_mfma_f32_16x16x32_bf16 v[30:33], v[180:183], v[228:231], v[30:33]
	v_mfma_f32_16x16x32_bf16 v[18:21], v[138:141], v[236:239], v[18:21]
	v_mfma_f32_16x16x32_bf16 v[14:17], v[180:183], v[236:239], v[14:17]
	v_mfma_f32_16x16x32_bf16 v[58:61], v[184:187], v[208:211], v[58:61]
	v_mfma_f32_16x16x32_bf16 v[54:57], v[192:195], v[208:211], v[54:57]
	v_mfma_f32_16x16x32_bf16 v[42:45], v[184:187], v[216:219], v[42:45]
	v_mfma_f32_16x16x32_bf16 v[38:41], v[192:195], v[216:219], v[38:41]
	v_mfma_f32_16x16x32_bf16 v[26:29], v[184:187], v[224:227], v[26:29]
	v_mfma_f32_16x16x32_bf16 v[22:25], v[192:195], v[224:227], v[22:25]
	v_mfma_f32_16x16x32_bf16 v[10:13], v[184:187], v[232:235], v[10:13]
	v_mfma_f32_16x16x32_bf16 v[4:7], v[192:195], v[232:235], v[6:9]
	v_mfma_f32_16x16x32_bf16 v[58:61], v[188:191], v[212:215], v[58:61]
	v_mfma_f32_16x16x32_bf16 v[54:57], v[196:199], v[212:215], v[54:57]
	v_mfma_f32_16x16x32_bf16 v[42:45], v[188:191], v[220:223], v[42:45]
	v_mfma_f32_16x16x32_bf16 v[38:41], v[196:199], v[220:223], v[38:41]
	v_mfma_f32_16x16x32_bf16 v[26:29], v[188:191], v[228:231], v[26:29]
	v_mfma_f32_16x16x32_bf16 v[22:25], v[196:199], v[228:231], v[22:25]
	v_mfma_f32_16x16x32_bf16 v[10:13], v[188:191], v[236:239], v[10:13]
	v_mfma_f32_16x16x32_bf16 v[4:7], v[196:199], v[236:239], v[4:7]
	s_barrier
	s_add_i32 s48, 0, 0x18000
	v_add_u32_e32 v2, s48, v1
	s_add_i32 s49, 0, 0x1c000
	ds_read_b128 v[134:137], v2
	ds_read_b128 v[138:141], v2 offset:1024
	ds_read_b128 v[142:145], v2 offset:2048
	ds_read_b128 v[180:183], v2 offset:3072
	v_add_u32_e32 v2, s49, v1
	ds_read_b128 v[184:187], v2
	ds_read_b128 v[188:191], v2 offset:1024
	ds_read_b128 v[192:195], v2 offset:2048
	ds_read_b128 v[196:199], v2 offset:3072
	s_add_u32 s24, s24, 0x80000
	s_addc_u32 s25, s25, 0
	s_mov_b32 m0, s38
	v_lshl_add_u64 v[8:9], s[24:25], 0, v[152:153]
	ds_read_b128 v[208:211], v163 offset:32768
	ds_read_b128 v[212:215], v163 offset:33792
	ds_read_b128 v[216:219], v163 offset:34816
	ds_read_b128 v[220:223], v163 offset:35840
	ds_read_b128 v[224:227], v163 offset:36864
	ds_read_b128 v[228:231], v163 offset:37888
	ds_read_b128 v[232:235], v163 offset:38912
	ds_read_b128 v[236:239], v163 offset:39936
	global_load_lds_dwordx4 v[8:9], off
	v_lshl_add_u64 v[8:9], s[24:25], 0, v[148:149]
	s_mov_b32 m0, s39
	s_nop 0
	global_load_lds_dwordx4 v[8:9], off
	s_waitcnt vmcnt(8)
	s_waitcnt lgkmcnt(0)
	s_barrier
	s_waitcnt lgkmcnt(0)
	v_mfma_f32_16x16x32_bf16 v[130:133], v[134:137], v[208:211], v[130:133]
	v_mfma_f32_16x16x32_bf16 v[126:129], v[142:145], v[208:211], v[126:129]
	v_mfma_f32_16x16x32_bf16 v[118:121], v[134:137], v[216:219], v[118:121]
	v_mfma_f32_16x16x32_bf16 v[110:113], v[142:145], v[216:219], v[110:113]
	v_mfma_f32_16x16x32_bf16 v[98:101], v[134:137], v[224:227], v[98:101]
	v_mfma_f32_16x16x32_bf16 v[94:97], v[142:145], v[224:227], v[94:97]
	v_mfma_f32_16x16x32_bf16 v[82:85], v[134:137], v[232:235], v[82:85]
	v_mfma_f32_16x16x32_bf16 v[78:81], v[142:145], v[232:235], v[78:81]
	v_mfma_f32_16x16x32_bf16 v[130:133], v[138:141], v[212:215], v[130:133]
	v_mfma_f32_16x16x32_bf16 v[126:129], v[180:183], v[212:215], v[126:129]
	v_mfma_f32_16x16x32_bf16 v[118:121], v[138:141], v[220:223], v[118:121]
	v_mfma_f32_16x16x32_bf16 v[110:113], v[180:183], v[220:223], v[110:113]
	v_mfma_f32_16x16x32_bf16 v[98:101], v[138:141], v[228:231], v[98:101]
	v_mfma_f32_16x16x32_bf16 v[94:97], v[180:183], v[228:231], v[94:97]
	v_mfma_f32_16x16x32_bf16 v[82:85], v[138:141], v[236:239], v[82:85]
	v_mfma_f32_16x16x32_bf16 v[78:81], v[180:183], v[236:239], v[78:81]
	v_mfma_f32_16x16x32_bf16 v[122:125], v[184:187], v[208:211], v[122:125]
	v_mfma_f32_16x16x32_bf16 v[114:117], v[192:195], v[208:211], v[114:117]
	v_mfma_f32_16x16x32_bf16 v[106:109], v[184:187], v[216:219], v[106:109]
	v_mfma_f32_16x16x32_bf16 v[102:105], v[192:195], v[216:219], v[102:105]
	v_mfma_f32_16x16x32_bf16 v[90:93], v[184:187], v[224:227], v[90:93]
	v_mfma_f32_16x16x32_bf16 v[86:89], v[192:195], v[224:227], v[86:89]
	v_mfma_f32_16x16x32_bf16 v[74:77], v[184:187], v[232:235], v[74:77]
	v_mfma_f32_16x16x32_bf16 v[70:73], v[192:195], v[232:235], v[70:73]
	v_mfma_f32_16x16x32_bf16 v[122:125], v[188:191], v[212:215], v[122:125]
	v_mfma_f32_16x16x32_bf16 v[114:117], v[196:199], v[212:215], v[114:117]
	v_mfma_f32_16x16x32_bf16 v[106:109], v[188:191], v[220:223], v[106:109]
	v_mfma_f32_16x16x32_bf16 v[102:105], v[196:199], v[220:223], v[102:105]
	v_mfma_f32_16x16x32_bf16 v[90:93], v[188:191], v[228:231], v[90:93]
	v_mfma_f32_16x16x32_bf16 v[86:89], v[196:199], v[228:231], v[86:89]
	v_mfma_f32_16x16x32_bf16 v[74:77], v[188:191], v[236:239], v[74:77]
	v_mfma_f32_16x16x32_bf16 v[70:73], v[196:199], v[236:239], v[70:73]
	s_barrier
	s_mov_b64 s[50:51], 0x80
	s_add_i32 s24, s48, s28
	v_lshl_add_u64 v[8:9], v[166:167], 0, s[50:51]
	s_mov_b32 m0, s24
	ds_read_b128 v[208:211], v163 offset:49152
	ds_read_b128 v[212:215], v163 offset:50176
	ds_read_b128 v[216:219], v163 offset:51200
	ds_read_b128 v[220:223], v163 offset:52224
	ds_read_b128 v[224:227], v163 offset:53248
	ds_read_b128 v[228:231], v163 offset:54272
	ds_read_b128 v[232:235], v163 offset:55296
	ds_read_b128 v[236:239], v163 offset:56320
	global_load_lds_dwordx4 v[8:9], off
	s_add_i32 m0, s24, 0x2000
	s_add_u32 s20, s20, 0x80080
	v_lshl_add_u64 v[8:9], v[240:241], 0, s[50:51]
	s_addc_u32 s21, s21, 0
	s_add_i32 s24, s49, s28
	global_load_lds_dwordx4 v[8:9], off
	v_lshl_add_u64 v[8:9], s[20:21], 0, v[150:151]
	s_mov_b32 m0, s24
	s_nop 0
	global_load_lds_dwordx4 v[8:9], off
	v_lshl_add_u64 v[8:9], s[20:21], 0, v[146:147]
	s_add_i32 m0, s24, 0x2000
	s_nop 0
	global_load_lds_dwordx4 v[8:9], off
	v_lshl_add_u64 v[8:9], v[242:243], 0, s[50:51]
	s_mov_b32 m0, s40
	s_nop 0
	global_load_lds_dwordx4 v[8:9], off
	v_lshl_add_u64 v[8:9], v[244:245], 0, s[50:51]
	s_mov_b32 m0, s41
	s_nop 0
	global_load_lds_dwordx4 v[8:9], off
	s_waitcnt vmcnt(8)
	s_waitcnt lgkmcnt(0)
	s_barrier
	s_waitcnt lgkmcnt(0)
	v_mfma_f32_16x16x32_bf16 v[66:69], v[134:137], v[208:211], v[66:69]
	v_mfma_f32_16x16x32_bf16 v[62:65], v[142:145], v[208:211], v[62:65]
	v_mfma_f32_16x16x32_bf16 v[50:53], v[134:137], v[216:219], v[50:53]
	v_mfma_f32_16x16x32_bf16 v[46:49], v[142:145], v[216:219], v[46:49]
	v_mfma_f32_16x16x32_bf16 v[34:37], v[134:137], v[224:227], v[34:37]
	v_mfma_f32_16x16x32_bf16 v[30:33], v[142:145], v[224:227], v[30:33]
	v_mfma_f32_16x16x32_bf16 v[18:21], v[134:137], v[232:235], v[18:21]
	v_mfma_f32_16x16x32_bf16 v[14:17], v[142:145], v[232:235], v[14:17]
	v_mfma_f32_16x16x32_bf16 v[66:69], v[138:141], v[212:215], v[66:69]
	v_mfma_f32_16x16x32_bf16 v[62:65], v[180:183], v[212:215], v[62:65]
	v_mfma_f32_16x16x32_bf16 v[50:53], v[138:141], v[220:223], v[50:53]
	v_mfma_f32_16x16x32_bf16 v[46:49], v[180:183], v[220:223], v[46:49]
	v_mfma_f32_16x16x32_bf16 v[34:37], v[138:141], v[228:231], v[34:37]
	v_mfma_f32_16x16x32_bf16 v[30:33], v[180:183], v[228:231], v[30:33]
	v_mfma_f32_16x16x32_bf16 v[18:21], v[138:141], v[236:239], v[18:21]
	v_mfma_f32_16x16x32_bf16 v[14:17], v[180:183], v[236:239], v[14:17]
	v_mfma_f32_16x16x32_bf16 v[58:61], v[184:187], v[208:211], v[58:61]
	v_mfma_f32_16x16x32_bf16 v[54:57], v[192:195], v[208:211], v[54:57]
	v_mfma_f32_16x16x32_bf16 v[42:45], v[184:187], v[216:219], v[42:45]
	v_mfma_f32_16x16x32_bf16 v[38:41], v[192:195], v[216:219], v[38:41]
	v_mfma_f32_16x16x32_bf16 v[26:29], v[184:187], v[224:227], v[26:29]
	v_mfma_f32_16x16x32_bf16 v[22:25], v[192:195], v[224:227], v[22:25]
	v_mfma_f32_16x16x32_bf16 v[8:11], v[184:187], v[232:235], v[10:13]
	v_mfma_f32_16x16x32_bf16 v[4:7], v[192:195], v[232:235], v[4:7]
	v_mfma_f32_16x16x32_bf16 v[58:61], v[188:191], v[212:215], v[58:61]
	v_mfma_f32_16x16x32_bf16 v[54:57], v[196:199], v[212:215], v[54:57]
	v_mfma_f32_16x16x32_bf16 v[42:45], v[188:191], v[220:223], v[42:45]
	v_mfma_f32_16x16x32_bf16 v[38:41], v[196:199], v[220:223], v[38:41]
	v_mfma_f32_16x16x32_bf16 v[26:29], v[188:191], v[228:231], v[26:29]
	v_mfma_f32_16x16x32_bf16 v[22:25], v[196:199], v[228:231], v[22:25]
	v_mfma_f32_16x16x32_bf16 v[10:13], v[188:191], v[236:239], v[8:11]
	v_mfma_f32_16x16x32_bf16 v[6:9], v[196:199], v[236:239], v[4:7]
	s_barrier
	s_add_i32 s47, s47, 2
	s_add_u32 s18, s18, 0x100
	s_addc_u32 s19, s19, 0
	s_cmp_gt_u32 s47, 29
	s_cbranch_scc1 .LBB0_1015

.LBB0_1087:
	s_add_i32 s52, s20, 2
	s_add_u32 s21, s18, 0xfff80080
	s_addc_u32 s24, s19, -1
	s_add_i32 s53, 0, 0x10000
	s_cmp_eq_u32 s9, s20
	s_cselect_b32 s25, s11, s24
	s_cselect_b32 s24, s10, s21
	v_add_u32_e32 v2, s53, v1
	s_cselect_b32 s21, s17, s51
	s_cselect_b32 s20, s16, s15
	s_add_i32 s56, 0, 0x14000
	ds_read_b128 v[146:149], v2
	ds_read_b128 v[150:153], v2 offset:1024
	ds_read_b128 v[154:157], v2 offset:2048
	ds_read_b128 v[158:161], v2 offset:3072
	v_add_u32_e32 v2, s56, v1
	ds_read_b128 v[162:165], v2
	ds_read_b128 v[180:183], v2 offset:1024
	ds_read_b128 v[184:187], v2 offset:2048
	ds_read_b128 v[188:191], v2 offset:3072
	v_lshl_add_u64 v[166:167], s[18:19], 0, v[140:141]
	s_add_i32 m0, s34, 0xc000
	ds_read_b128 v[192:195], v145
	ds_read_b128 v[196:199], v145 offset:1024
	ds_read_b128 v[208:211], v145 offset:2048
	ds_read_b128 v[212:215], v145 offset:3072
	ds_read_b128 v[216:219], v145 offset:4096
	ds_read_b128 v[220:223], v145 offset:5120
	ds_read_b128 v[224:227], v145 offset:6144
	ds_read_b128 v[228:231], v145 offset:7168
	global_load_lds_dwordx4 v[166:167], off
	v_lshl_add_u64 v[166:167], s[18:19], 0, v[142:143]
	s_add_i32 m0, s34, 0xe000
	s_nop 0
	global_load_lds_dwordx4 v[166:167], off
	s_waitcnt vmcnt(8)
	s_waitcnt lgkmcnt(0)
	s_barrier
	s_waitcnt lgkmcnt(0)
	v_mfma_f32_16x16x32_bf16 v[128:131], v[146:149], v[192:195], v[128:131]
	v_mfma_f32_16x16x32_bf16 v[124:127], v[154:157], v[192:195], v[124:127]
	v_mfma_f32_16x16x32_bf16 v[120:123], v[146:149], v[208:211], v[120:123]
	v_mfma_f32_16x16x32_bf16 v[112:115], v[154:157], v[208:211], v[112:115]
	v_mfma_f32_16x16x32_bf16 v[104:107], v[146:149], v[216:219], v[104:107]
	v_mfma_f32_16x16x32_bf16 v[96:99], v[154:157], v[216:219], v[96:99]
	v_mfma_f32_16x16x32_bf16 v[88:91], v[146:149], v[224:227], v[88:91]
	v_mfma_f32_16x16x32_bf16 v[80:83], v[154:157], v[224:227], v[80:83]
	v_mfma_f32_16x16x32_bf16 v[128:131], v[150:153], v[196:199], v[128:131]
	v_mfma_f32_16x16x32_bf16 v[124:127], v[158:161], v[196:199], v[124:127]
	v_mfma_f32_16x16x32_bf16 v[120:123], v[150:153], v[212:215], v[120:123]
	v_mfma_f32_16x16x32_bf16 v[112:115], v[158:161], v[212:215], v[112:115]
	v_mfma_f32_16x16x32_bf16 v[104:107], v[150:153], v[220:223], v[104:107]
	v_mfma_f32_16x16x32_bf16 v[96:99], v[158:161], v[220:223], v[96:99]
	v_mfma_f32_16x16x32_bf16 v[88:91], v[150:153], v[228:231], v[88:91]
	v_mfma_f32_16x16x32_bf16 v[80:83], v[158:161], v[228:231], v[80:83]
	v_mfma_f32_16x16x32_bf16 v[116:119], v[162:165], v[192:195], v[116:119]
	v_mfma_f32_16x16x32_bf16 v[108:111], v[184:187], v[192:195], v[108:111]
	v_mfma_f32_16x16x32_bf16 v[100:103], v[162:165], v[208:211], v[100:103]
	v_mfma_f32_16x16x32_bf16 v[92:95], v[184:187], v[208:211], v[92:95]
	v_mfma_f32_16x16x32_bf16 v[84:87], v[162:165], v[216:219], v[84:87]
	v_mfma_f32_16x16x32_bf16 v[76:79], v[184:187], v[216:219], v[76:79]
	v_mfma_f32_16x16x32_bf16 v[72:75], v[162:165], v[224:227], v[72:75]
	v_mfma_f32_16x16x32_bf16 v[68:71], v[184:187], v[224:227], v[68:71]
	v_mfma_f32_16x16x32_bf16 v[116:119], v[180:183], v[196:199], v[116:119]
	v_mfma_f32_16x16x32_bf16 v[108:111], v[188:191], v[196:199], v[108:111]
	v_mfma_f32_16x16x32_bf16 v[100:103], v[180:183], v[212:215], v[100:103]
	v_mfma_f32_16x16x32_bf16 v[92:95], v[188:191], v[212:215], v[92:95]
	v_mfma_f32_16x16x32_bf16 v[84:87], v[180:183], v[220:223], v[84:87]
	v_mfma_f32_16x16x32_bf16 v[76:79], v[188:191], v[220:223], v[76:79]
	v_mfma_f32_16x16x32_bf16 v[72:75], v[180:183], v[228:231], v[72:75]
	v_mfma_f32_16x16x32_bf16 v[68:71], v[188:191], v[228:231], v[68:71]
	s_barrier
	s_add_i32 s53, s53, s28
	v_lshl_add_u64 v[166:167], s[20:21], 0, v[136:137]
	s_mov_b32 m0, s53
	ds_read_b128 v[192:195], v145 offset:16384
	ds_read_b128 v[196:199], v145 offset:17408
	ds_read_b128 v[208:211], v145 offset:18432
	ds_read_b128 v[212:215], v145 offset:19456
	ds_read_b128 v[216:219], v145 offset:20480
	ds_read_b128 v[220:223], v145 offset:21504
	ds_read_b128 v[224:227], v145 offset:22528
	ds_read_b128 v[228:231], v145 offset:23552
	global_load_lds_dwordx4 v[166:167], off
	s_add_i32 m0, s53, 0x2000
	s_add_u32 s54, s20, 0x80000
	v_lshl_add_u64 v[232:233], s[20:21], 0, v[132:133]
	s_addc_u32 s55, s21, 0
	s_add_i32 s53, s56, s28
	global_load_lds_dwordx4 v[232:233], off
	v_lshl_add_u64 v[234:235], s[54:55], 0, v[136:137]
	s_mov_b32 m0, s53
	v_lshl_add_u64 v[236:237], s[24:25], 0, v[134:135]
	global_load_lds_dwordx4 v[234:235], off
	v_lshl_add_u64 v[234:235], s[54:55], 0, v[132:133]
	s_add_i32 m0, s53, 0x2000
	s_nop 0
	global_load_lds_dwordx4 v[234:235], off
	v_lshl_add_u64 v[234:235], s[24:25], 0, v[138:139]
	s_mov_b32 m0, s34
	s_nop 0
	global_load_lds_dwordx4 v[234:235], off
	s_mov_b32 m0, s35
	s_nop 0
	global_load_lds_dwordx4 v[236:237], off
	s_waitcnt vmcnt(8)
	s_waitcnt lgkmcnt(0)
	s_barrier
	s_waitcnt lgkmcnt(0)
	v_mfma_f32_16x16x32_bf16 v[64:67], v[146:149], v[192:195], v[64:67]
	v_mfma_f32_16x16x32_bf16 v[60:63], v[154:157], v[192:195], v[60:63]
	v_mfma_f32_16x16x32_bf16 v[56:59], v[146:149], v[208:211], v[56:59]
	v_mfma_f32_16x16x32_bf16 v[48:51], v[154:157], v[208:211], v[48:51]
	v_mfma_f32_16x16x32_bf16 v[40:43], v[146:149], v[216:219], v[40:43]
	v_mfma_f32_16x16x32_bf16 v[32:35], v[154:157], v[216:219], v[32:35]
	v_mfma_f32_16x16x32_bf16 v[24:27], v[146:149], v[224:227], v[24:27]
	v_mfma_f32_16x16x32_bf16 v[16:19], v[154:157], v[224:227], v[16:19]
	v_mfma_f32_16x16x32_bf16 v[64:67], v[150:153], v[196:199], v[64:67]
	v_mfma_f32_16x16x32_bf16 v[60:63], v[158:161], v[196:199], v[60:63]
	v_mfma_f32_16x16x32_bf16 v[56:59], v[150:153], v[212:215], v[56:59]
	v_mfma_f32_16x16x32_bf16 v[48:51], v[158:161], v[212:215], v[48:51]
	v_mfma_f32_16x16x32_bf16 v[40:43], v[150:153], v[220:223], v[40:43]
	v_mfma_f32_16x16x32_bf16 v[32:35], v[158:161], v[220:223], v[32:35]
	v_mfma_f32_16x16x32_bf16 v[24:27], v[150:153], v[228:231], v[24:27]
	v_mfma_f32_16x16x32_bf16 v[16:19], v[158:161], v[228:231], v[16:19]
	v_mfma_f32_16x16x32_bf16 v[52:55], v[162:165], v[192:195], v[52:55]
	v_mfma_f32_16x16x32_bf16 v[44:47], v[184:187], v[192:195], v[44:47]
	v_mfma_f32_16x16x32_bf16 v[36:39], v[162:165], v[208:211], v[36:39]
	v_mfma_f32_16x16x32_bf16 v[28:31], v[184:187], v[208:211], v[28:31]
	v_mfma_f32_16x16x32_bf16 v[20:23], v[162:165], v[216:219], v[20:23]
	v_mfma_f32_16x16x32_bf16 v[12:15], v[184:187], v[216:219], v[12:15]
	v_mfma_f32_16x16x32_bf16 v[8:11], v[162:165], v[224:227], v[8:11]
	v_mfma_f32_16x16x32_bf16 v[4:7], v[184:187], v[224:227], v[4:7]
	v_mfma_f32_16x16x32_bf16 v[52:55], v[180:183], v[196:199], v[52:55]
	v_mfma_f32_16x16x32_bf16 v[44:47], v[188:191], v[196:199], v[44:47]
	v_mfma_f32_16x16x32_bf16 v[36:39], v[180:183], v[212:215], v[36:39]
	v_mfma_f32_16x16x32_bf16 v[28:31], v[188:191], v[212:215], v[28:31]
	v_mfma_f32_16x16x32_bf16 v[20:23], v[180:183], v[220:223], v[20:23]
	v_mfma_f32_16x16x32_bf16 v[12:15], v[188:191], v[220:223], v[12:15]
	v_mfma_f32_16x16x32_bf16 v[8:11], v[180:183], v[228:231], v[8:11]
	v_mfma_f32_16x16x32_bf16 v[4:7], v[188:191], v[228:231], v[4:7]
	s_barrier
	s_add_i32 s53, 0, 0x18000
	v_add_u32_e32 v2, s53, v1
	s_add_i32 s54, 0, 0x1c000
	ds_read_b128 v[146:149], v2
	ds_read_b128 v[150:153], v2 offset:1024
	ds_read_b128 v[154:157], v2 offset:2048
	ds_read_b128 v[158:161], v2 offset:3072
	v_add_u32_e32 v2, s54, v1
	ds_read_b128 v[162:165], v2
	ds_read_b128 v[180:183], v2 offset:1024
	ds_read_b128 v[184:187], v2 offset:2048
	ds_read_b128 v[188:191], v2 offset:3072
	s_add_u32 s24, s24, 0x80000
	s_addc_u32 s25, s25, 0
	s_mov_b32 m0, s40
	v_lshl_add_u64 v[238:239], s[24:25], 0, v[138:139]
	ds_read_b128 v[192:195], v145 offset:32768
	ds_read_b128 v[196:199], v145 offset:33792
	ds_read_b128 v[208:211], v145 offset:34816
	ds_read_b128 v[212:215], v145 offset:35840
	ds_read_b128 v[216:219], v145 offset:36864
	ds_read_b128 v[220:223], v145 offset:37888
	ds_read_b128 v[224:227], v145 offset:38912
	ds_read_b128 v[228:231], v145 offset:39936
	global_load_lds_dwordx4 v[238:239], off
	v_lshl_add_u64 v[238:239], s[24:25], 0, v[134:135]
	s_mov_b32 m0, s41
	s_nop 0
	global_load_lds_dwordx4 v[238:239], off
	s_waitcnt vmcnt(8)
	s_waitcnt lgkmcnt(0)
	s_barrier
	s_waitcnt lgkmcnt(0)
	v_mfma_f32_16x16x32_bf16 v[128:131], v[146:149], v[192:195], v[128:131]
	v_mfma_f32_16x16x32_bf16 v[124:127], v[154:157], v[192:195], v[124:127]
	v_mfma_f32_16x16x32_bf16 v[120:123], v[146:149], v[208:211], v[120:123]
	v_mfma_f32_16x16x32_bf16 v[112:115], v[154:157], v[208:211], v[112:115]
	v_mfma_f32_16x16x32_bf16 v[104:107], v[146:149], v[216:219], v[104:107]
	v_mfma_f32_16x16x32_bf16 v[96:99], v[154:157], v[216:219], v[96:99]
	v_mfma_f32_16x16x32_bf16 v[88:91], v[146:149], v[224:227], v[88:91]
	v_mfma_f32_16x16x32_bf16 v[80:83], v[154:157], v[224:227], v[80:83]
	v_mfma_f32_16x16x32_bf16 v[128:131], v[150:153], v[196:199], v[128:131]
	v_mfma_f32_16x16x32_bf16 v[124:127], v[158:161], v[196:199], v[124:127]
	v_mfma_f32_16x16x32_bf16 v[120:123], v[150:153], v[212:215], v[120:123]
	v_mfma_f32_16x16x32_bf16 v[112:115], v[158:161], v[212:215], v[112:115]
	v_mfma_f32_16x16x32_bf16 v[104:107], v[150:153], v[220:223], v[104:107]
	v_mfma_f32_16x16x32_bf16 v[96:99], v[158:161], v[220:223], v[96:99]
	v_mfma_f32_16x16x32_bf16 v[88:91], v[150:153], v[228:231], v[88:91]
	v_mfma_f32_16x16x32_bf16 v[80:83], v[158:161], v[228:231], v[80:83]
	v_mfma_f32_16x16x32_bf16 v[116:119], v[162:165], v[192:195], v[116:119]
	v_mfma_f32_16x16x32_bf16 v[108:111], v[184:187], v[192:195], v[108:111]
	v_mfma_f32_16x16x32_bf16 v[100:103], v[162:165], v[208:211], v[100:103]
	v_mfma_f32_16x16x32_bf16 v[92:95], v[184:187], v[208:211], v[92:95]
	v_mfma_f32_16x16x32_bf16 v[84:87], v[162:165], v[216:219], v[84:87]
	v_mfma_f32_16x16x32_bf16 v[76:79], v[184:187], v[216:219], v[76:79]
	v_mfma_f32_16x16x32_bf16 v[72:75], v[162:165], v[224:227], v[72:75]
	v_mfma_f32_16x16x32_bf16 v[68:71], v[184:187], v[224:227], v[68:71]
	v_mfma_f32_16x16x32_bf16 v[116:119], v[180:183], v[196:199], v[116:119]
	v_mfma_f32_16x16x32_bf16 v[108:111], v[188:191], v[196:199], v[108:111]
	v_mfma_f32_16x16x32_bf16 v[100:103], v[180:183], v[212:215], v[100:103]
	v_mfma_f32_16x16x32_bf16 v[92:95], v[188:191], v[212:215], v[92:95]
	v_mfma_f32_16x16x32_bf16 v[84:87], v[180:183], v[220:223], v[84:87]
	v_mfma_f32_16x16x32_bf16 v[76:79], v[188:191], v[220:223], v[76:79]
	v_mfma_f32_16x16x32_bf16 v[72:75], v[180:183], v[228:231], v[72:75]
	v_mfma_f32_16x16x32_bf16 v[68:71], v[188:191], v[228:231], v[68:71]
	s_barrier
	s_add_i32 s24, s53, s28
	v_lshl_add_u64 v[166:167], v[166:167], 0, s[2:3]
	s_mov_b32 m0, s24
	ds_read_b128 v[192:195], v145 offset:49152
	ds_read_b128 v[196:199], v145 offset:50176
	ds_read_b128 v[208:211], v145 offset:51200
	ds_read_b128 v[212:215], v145 offset:52224
	ds_read_b128 v[216:219], v145 offset:53248
	ds_read_b128 v[220:223], v145 offset:54272
	ds_read_b128 v[224:227], v145 offset:55296
	ds_read_b128 v[228:231], v145 offset:56320
	global_load_lds_dwordx4 v[166:167], off
	s_add_i32 m0, s24, 0x2000
	s_add_u32 s20, s20, 0x80080
	v_lshl_add_u64 v[166:167], v[232:233], 0, s[2:3]
	s_addc_u32 s21, s21, 0
	s_add_i32 s24, s54, s28
	global_load_lds_dwordx4 v[166:167], off
	v_lshl_add_u64 v[166:167], s[20:21], 0, v[136:137]
	s_mov_b32 m0, s24
	s_nop 0
	global_load_lds_dwordx4 v[166:167], off
	v_lshl_add_u64 v[166:167], s[20:21], 0, v[132:133]
	s_add_i32 m0, s24, 0x2000
	s_nop 0
	global_load_lds_dwordx4 v[166:167], off
	v_lshl_add_u64 v[166:167], v[234:235], 0, s[2:3]
	s_mov_b32 m0, s42
	s_nop 0
	global_load_lds_dwordx4 v[166:167], off
	v_lshl_add_u64 v[166:167], v[236:237], 0, s[2:3]
	s_mov_b32 m0, s43
	s_nop 0
	global_load_lds_dwordx4 v[166:167], off
	s_waitcnt vmcnt(8)
	s_waitcnt lgkmcnt(0)
	s_barrier
	s_waitcnt lgkmcnt(0)
	v_mfma_f32_16x16x32_bf16 v[64:67], v[146:149], v[192:195], v[64:67]
	v_mfma_f32_16x16x32_bf16 v[60:63], v[154:157], v[192:195], v[60:63]
	v_mfma_f32_16x16x32_bf16 v[56:59], v[146:149], v[208:211], v[56:59]
	v_mfma_f32_16x16x32_bf16 v[48:51], v[154:157], v[208:211], v[48:51]
	v_mfma_f32_16x16x32_bf16 v[40:43], v[146:149], v[216:219], v[40:43]
	v_mfma_f32_16x16x32_bf16 v[32:35], v[154:157], v[216:219], v[32:35]
	v_mfma_f32_16x16x32_bf16 v[24:27], v[146:149], v[224:227], v[24:27]
	v_mfma_f32_16x16x32_bf16 v[16:19], v[154:157], v[224:227], v[16:19]
	v_mfma_f32_16x16x32_bf16 v[64:67], v[150:153], v[196:199], v[64:67]
	v_mfma_f32_16x16x32_bf16 v[60:63], v[158:161], v[196:199], v[60:63]
	v_mfma_f32_16x16x32_bf16 v[56:59], v[150:153], v[212:215], v[56:59]
	v_mfma_f32_16x16x32_bf16 v[48:51], v[158:161], v[212:215], v[48:51]
	v_mfma_f32_16x16x32_bf16 v[40:43], v[150:153], v[220:223], v[40:43]
	v_mfma_f32_16x16x32_bf16 v[32:35], v[158:161], v[220:223], v[32:35]
	v_mfma_f32_16x16x32_bf16 v[24:27], v[150:153], v[228:231], v[24:27]
	v_mfma_f32_16x16x32_bf16 v[16:19], v[158:161], v[228:231], v[16:19]
	v_mfma_f32_16x16x32_bf16 v[52:55], v[162:165], v[192:195], v[52:55]
	v_mfma_f32_16x16x32_bf16 v[44:47], v[184:187], v[192:195], v[44:47]
	v_mfma_f32_16x16x32_bf16 v[36:39], v[162:165], v[208:211], v[36:39]
	v_mfma_f32_16x16x32_bf16 v[28:31], v[184:187], v[208:211], v[28:31]
	v_mfma_f32_16x16x32_bf16 v[20:23], v[162:165], v[216:219], v[20:23]
	v_mfma_f32_16x16x32_bf16 v[12:15], v[184:187], v[216:219], v[12:15]
	v_mfma_f32_16x16x32_bf16 v[8:11], v[162:165], v[224:227], v[8:11]
	v_mfma_f32_16x16x32_bf16 v[4:7], v[184:187], v[224:227], v[4:7]
	v_mfma_f32_16x16x32_bf16 v[52:55], v[180:183], v[196:199], v[52:55]
	v_mfma_f32_16x16x32_bf16 v[44:47], v[188:191], v[196:199], v[44:47]
	v_mfma_f32_16x16x32_bf16 v[36:39], v[180:183], v[212:215], v[36:39]
	v_mfma_f32_16x16x32_bf16 v[28:31], v[188:191], v[212:215], v[28:31]
	v_mfma_f32_16x16x32_bf16 v[20:23], v[180:183], v[220:223], v[20:23]
	v_mfma_f32_16x16x32_bf16 v[12:15], v[188:191], v[220:223], v[12:15]
	v_mfma_f32_16x16x32_bf16 v[8:11], v[180:183], v[228:231], v[8:11]
	v_mfma_f32_16x16x32_bf16 v[4:7], v[188:191], v[228:231], v[4:7]
	s_barrier
	s_add_u32 s18, s18, 0x100
	s_addc_u32 s19, s19, 0
	s_add_u32 s15, s15, 0x100
	s_addc_u32 s51, s51, 0
	s_cmp_ge_u32 s52, s47
	s_mov_b32 s20, s52
	s_cbranch_scc0 .LBB0_1087
	s_and_b64 vcc, exec, s[6:7]
	s_cbranch_vccz .LBB0_1090
	s_barrier
.LBB0_1090:
	s_cmp_eq_u32 s47, 8
	s_cbranch_scc1 .Llast_out
	v_cvt_f32_u32_e32 v2, s47
	v_cvt_f32_u32_e32 v148, s50
	v_cvt_pk_bf16_f32 v146, v128, v129
	v_readlane_b32 s2, v250, 17
	v_rcp_iflag_f32_e32 v149, v2
	v_readlane_b32 s3, v250, 18
	v_cvt_pk_bf16_f32 v147, v130, v131
	v_readlane_b32 s54, v250, 52
	v_mul_f32_e32 v128, v148, v149
	v_trunc_f32_e32 v128, v128
	v_cvt_u32_f32_e32 v129, v128
	v_fma_f32 v128, -v128, v2, v148
	v_cmp_ge_f32_e64 s[18:19], |v128|, v2
	s_cmp_lg_u64 s[18:19], 0
	v_readfirstlane_b32 s9, v129
	s_addc_u32 s9, s9, 0
	s_and_b32 s9, s9, 0xff
	s_mul_hi_u32 s15, s9, 0x2800000
	s_mul_i32 s9, s9, 0x2800000
	s_add_u32 s18, s2, s9
	s_addc_u32 s19, s3, s15
	s_lshl_b32 s9, s49, 9
	s_lshl_b32 s15, s48, 20
	s_add_i32 s9, s9, s15
	v_add_u32_e32 v2, s9, v144
	v_lshl_add_u64 v[128:129], s[18:19], 0, v[2:3]
	s_mov_b32 s2, 0x10000
	v_cvt_pk_bf16_f32 v148, v124, v125
	v_cvt_pk_bf16_f32 v149, v126, v127
	global_store_dwordx4 v2, v[146:149], s[18:19]
	v_cvt_pk_bf16_f32 v116, v116, v117
	v_cvt_pk_bf16_f32 v117, v118, v119
	v_cvt_pk_bf16_f32 v118, v108, v109
	v_cvt_pk_bf16_f32 v119, v110, v111
	global_store_dwordx4 v2, v[116:119], s[18:19] offset:256
	v_cvt_pk_bf16_f32 v108, v120, v121
	v_cvt_pk_bf16_f32 v109, v122, v123
	v_cvt_pk_bf16_f32 v110, v112, v113
	v_add_co_u32_e32 v112, vcc, s2, v128
	v_cvt_pk_bf16_f32 v111, v114, v115
	s_mov_b32 s2, 0x30000
	s_nop 0
	v_addc_co_u32_e32 v113, vcc, 0, v129, vcc
	global_store_dwordx4 v[112:113], v[108:111], off
	v_cvt_pk_bf16_f32 v100, v100, v101
	v_cvt_pk_bf16_f32 v101, v102, v103
	v_cvt_pk_bf16_f32 v102, v92, v93
	v_cvt_pk_bf16_f32 v103, v94, v95
	global_store_dwordx4 v[112:113], v[100:103], off offset:256
	v_cvt_pk_bf16_f32 v92, v104, v105
	v_cvt_pk_bf16_f32 v93, v106, v107
	v_cvt_pk_bf16_f32 v94, v96, v97
	v_add_co_u32_e32 v96, vcc, s58, v128
	v_cvt_pk_bf16_f32 v95, v98, v99
	s_mov_b64 s[18:19], -1
	s_nop 0
	v_addc_co_u32_e32 v97, vcc, 0, v129, vcc
	global_store_dwordx4 v[96:97], v[92:95], off
	v_cvt_pk_bf16_f32 v84, v84, v85
	v_cvt_pk_bf16_f32 v85, v86, v87
	v_cvt_pk_bf16_f32 v86, v76, v77
	v_cvt_pk_bf16_f32 v87, v78, v79
	global_store_dwordx4 v[96:97], v[84:87], off offset:256
	v_cvt_pk_bf16_f32 v76, v88, v89
	v_cvt_pk_bf16_f32 v77, v90, v91
	v_cvt_pk_bf16_f32 v78, v80, v81
	v_add_co_u32_e32 v80, vcc, s2, v128
	s_mov_b32 s2, 0x80000
	s_nop 0
	v_addc_co_u32_e32 v81, vcc, 0, v129, vcc
	v_cvt_pk_bf16_f32 v79, v82, v83
	global_store_dwordx4 v[80:81], v[76:79], off
	v_cvt_pk_bf16_f32 v72, v72, v73
	v_cvt_pk_bf16_f32 v73, v74, v75
	v_cvt_pk_bf16_f32 v74, v68, v69
	v_cvt_pk_bf16_f32 v75, v70, v71
	global_store_dwordx4 v[80:81], v[72:75], off offset:256
	v_cvt_pk_bf16_f32 v64, v64, v65
	v_cvt_pk_bf16_f32 v65, v66, v67
	v_cvt_pk_bf16_f32 v66, v60, v61
	v_add_co_u32_e32 v60, vcc, s2, v128
	s_mov_b32 s2, 0x90000
	s_nop 0
	v_addc_co_u32_e32 v61, vcc, 0, v129, vcc
	v_cvt_pk_bf16_f32 v67, v62, v63
	global_store_dwordx4 v[60:61], v[64:67], off
	v_cvt_pk_bf16_f32 v52, v52, v53
	v_cvt_pk_bf16_f32 v53, v54, v55
	v_cvt_pk_bf16_f32 v54, v44, v45
	v_cvt_pk_bf16_f32 v55, v46, v47
	global_store_dwordx4 v[60:61], v[52:55], off offset:256
	v_cvt_pk_bf16_f32 v44, v56, v57
	v_cvt_pk_bf16_f32 v45, v58, v59
	v_cvt_pk_bf16_f32 v46, v48, v49
	v_add_co_u32_e32 v48, vcc, s2, v128
	s_mov_b32 s2, 0xa0000
	s_nop 0
	v_addc_co_u32_e32 v49, vcc, 0, v129, vcc
	v_cvt_pk_bf16_f32 v47, v50, v51
	global_store_dwordx4 v[48:49], v[44:47], off
	v_cvt_pk_bf16_f32 v36, v36, v37
	v_cvt_pk_bf16_f32 v37, v38, v39
	v_cvt_pk_bf16_f32 v38, v28, v29
	v_cvt_pk_bf16_f32 v39, v30, v31
	global_store_dwordx4 v[48:49], v[36:39], off offset:256
	v_cvt_pk_bf16_f32 v28, v40, v41
	v_cvt_pk_bf16_f32 v29, v42, v43
	v_cvt_pk_bf16_f32 v30, v32, v33
	v_add_co_u32_e32 v32, vcc, s2, v128
	s_mov_b32 s2, 0xb0000
	s_nop 0
	v_addc_co_u32_e32 v33, vcc, 0, v129, vcc
	v_cvt_pk_bf16_f32 v31, v34, v35
	global_store_dwordx4 v[32:33], v[28:31], off
	v_cvt_pk_bf16_f32 v20, v20, v21
	v_cvt_pk_bf16_f32 v21, v22, v23
	v_cvt_pk_bf16_f32 v22, v12, v13
	v_cvt_pk_bf16_f32 v23, v14, v15
	global_store_dwordx4 v[32:33], v[20:23], off offset:256
	v_cvt_pk_bf16_f32 v12, v24, v25
	v_cvt_pk_bf16_f32 v13, v26, v27
	v_cvt_pk_bf16_f32 v14, v16, v17
	v_add_co_u32_e32 v16, vcc, s2, v128
	s_mov_b64 s[56:57], 0x40000
	s_nop 0
	v_addc_co_u32_e32 v17, vcc, 0, v129, vcc
	s_and_b64 vcc, exec, s[38:39]
	v_readlane_b32 s55, v250, 53
	v_cvt_pk_bf16_f32 v15, v18, v19
	global_store_dwordx4 v[16:17], v[12:15], off
	v_cvt_pk_bf16_f32 v8, v8, v9
	v_cvt_pk_bf16_f32 v9, v10, v11
	v_cvt_pk_bf16_f32 v10, v4, v5
	v_cvt_pk_bf16_f32 v11, v6, v7
	global_store_dwordx4 v[16:17], v[8:11], off offset:256
.Ljoin_out:
	s_cbranch_vccnz .LBB0_1079
	s_and_b64 s[12:13], s[12:13], exec
	s_cselect_b32 s47, 8, s45
	s_andn2_b64 vcc, exec, s[0:1]
	s_cbranch_vccnz .LBB0_1078
	s_barrier
	s_branch .LBB0_1078
.Llast_out:
	v_cvt_f32_u32_e32 v2, s47
	v_cvt_f32_u32_e32 v148, s50
	v_cvt_pk_bf16_f32 v146, v128, v129
	v_readlane_b32 s2, v250, 17
	v_rcp_iflag_f32_e32 v149, v2
	v_readlane_b32 s3, v250, 18
	v_cvt_pk_bf16_f32 v147, v130, v131
	v_readlane_b32 s54, v250, 52
	v_mul_f32_e32 v128, v148, v149
	v_trunc_f32_e32 v128, v128
	v_cvt_u32_f32_e32 v129, v128
	v_fma_f32 v128, -v128, v2, v148
	v_cmp_ge_f32_e64 s[18:19], |v128|, v2
	s_cmp_lg_u64 s[18:19], 0
	v_readfirstlane_b32 s9, v129
	s_addc_u32 s9, s9, 0
	s_and_b32 s9, s9, 0xff
	s_mul_hi_u32 s15, s9, 0x2800000
	s_mul_i32 s9, s9, 0x2800000
	s_add_u32 s18, s2, s9
	s_addc_u32 s19, s3, s15
	s_lshl_b32 s9, s49, 9
	s_lshl_b32 s15, s48, 20
	s_add_i32 s9, s9, s15
	v_add_u32_e32 v2, s9, v144
	v_lshl_add_u64 v[128:129], s[18:19], 0, v[2:3]
	s_mov_b32 s2, 0x10000
	v_cvt_pk_bf16_f32 v148, v124, v125
	v_cvt_pk_bf16_f32 v149, v126, v127
	global_store_dwordx4 v2, v[146:149], s[18:19] sc0 sc1
	v_cvt_pk_bf16_f32 v116, v116, v117
	v_cvt_pk_bf16_f32 v117, v118, v119
	v_cvt_pk_bf16_f32 v118, v108, v109
	v_cvt_pk_bf16_f32 v119, v110, v111
	global_store_dwordx4 v2, v[116:119], s[18:19] offset:256 sc0 sc1
	v_cvt_pk_bf16_f32 v108, v120, v121
	v_cvt_pk_bf16_f32 v109, v122, v123
	v_cvt_pk_bf16_f32 v110, v112, v113
	v_add_co_u32_e32 v112, vcc, s2, v128
	v_cvt_pk_bf16_f32 v111, v114, v115
	s_mov_b32 s2, 0x30000
	s_nop 0
	v_addc_co_u32_e32 v113, vcc, 0, v129, vcc
	global_store_dwordx4 v[112:113], v[108:111], off sc0 sc1
	v_cvt_pk_bf16_f32 v100, v100, v101
	v_cvt_pk_bf16_f32 v101, v102, v103
	v_cvt_pk_bf16_f32 v102, v92, v93
	v_cvt_pk_bf16_f32 v103, v94, v95
	global_store_dwordx4 v[112:113], v[100:103], off offset:256 sc0 sc1
	v_cvt_pk_bf16_f32 v92, v104, v105
	v_cvt_pk_bf16_f32 v93, v106, v107
	v_cvt_pk_bf16_f32 v94, v96, v97
	v_add_co_u32_e32 v96, vcc, s58, v128
	v_cvt_pk_bf16_f32 v95, v98, v99
	s_mov_b64 s[18:19], -1
	s_nop 0
	v_addc_co_u32_e32 v97, vcc, 0, v129, vcc
	global_store_dwordx4 v[96:97], v[92:95], off sc0 sc1
	v_cvt_pk_bf16_f32 v84, v84, v85
	v_cvt_pk_bf16_f32 v85, v86, v87
	v_cvt_pk_bf16_f32 v86, v76, v77
	v_cvt_pk_bf16_f32 v87, v78, v79
	global_store_dwordx4 v[96:97], v[84:87], off offset:256 sc0 sc1
	v_cvt_pk_bf16_f32 v76, v88, v89
	v_cvt_pk_bf16_f32 v77, v90, v91
	v_cvt_pk_bf16_f32 v78, v80, v81
	v_add_co_u32_e32 v80, vcc, s2, v128
	s_mov_b32 s2, 0x80000
	s_nop 0
	v_addc_co_u32_e32 v81, vcc, 0, v129, vcc
	v_cvt_pk_bf16_f32 v79, v82, v83
	global_store_dwordx4 v[80:81], v[76:79], off sc0 sc1
	v_cvt_pk_bf16_f32 v72, v72, v73
	v_cvt_pk_bf16_f32 v73, v74, v75
	v_cvt_pk_bf16_f32 v74, v68, v69
	v_cvt_pk_bf16_f32 v75, v70, v71
	global_store_dwordx4 v[80:81], v[72:75], off offset:256 sc0 sc1
	v_cvt_pk_bf16_f32 v64, v64, v65
	v_cvt_pk_bf16_f32 v65, v66, v67
	v_cvt_pk_bf16_f32 v66, v60, v61
	v_add_co_u32_e32 v60, vcc, s2, v128
	s_mov_b32 s2, 0x90000
	s_nop 0
	v_addc_co_u32_e32 v61, vcc, 0, v129, vcc
	v_cvt_pk_bf16_f32 v67, v62, v63
	global_store_dwordx4 v[60:61], v[64:67], off sc0 sc1
	v_cvt_pk_bf16_f32 v52, v52, v53
	v_cvt_pk_bf16_f32 v53, v54, v55
	v_cvt_pk_bf16_f32 v54, v44, v45
	v_cvt_pk_bf16_f32 v55, v46, v47
	global_store_dwordx4 v[60:61], v[52:55], off offset:256 sc0 sc1
	v_cvt_pk_bf16_f32 v44, v56, v57
	v_cvt_pk_bf16_f32 v45, v58, v59
	v_cvt_pk_bf16_f32 v46, v48, v49
	v_add_co_u32_e32 v48, vcc, s2, v128
	s_mov_b32 s2, 0xa0000
	s_nop 0
	v_addc_co_u32_e32 v49, vcc, 0, v129, vcc
	v_cvt_pk_bf16_f32 v47, v50, v51
	global_store_dwordx4 v[48:49], v[44:47], off sc0 sc1
	v_cvt_pk_bf16_f32 v36, v36, v37
	v_cvt_pk_bf16_f32 v37, v38, v39
	v_cvt_pk_bf16_f32 v38, v28, v29
	v_cvt_pk_bf16_f32 v39, v30, v31
	global_store_dwordx4 v[48:49], v[36:39], off offset:256 sc0 sc1
	v_cvt_pk_bf16_f32 v28, v40, v41
	v_cvt_pk_bf16_f32 v29, v42, v43
	v_cvt_pk_bf16_f32 v30, v32, v33
	v_add_co_u32_e32 v32, vcc, s2, v128
	s_mov_b32 s2, 0xb0000
	s_nop 0
	v_addc_co_u32_e32 v33, vcc, 0, v129, vcc
	v_cvt_pk_bf16_f32 v31, v34, v35
	global_store_dwordx4 v[32:33], v[28:31], off sc0 sc1
	v_cvt_pk_bf16_f32 v20, v20, v21
	v_cvt_pk_bf16_f32 v21, v22, v23
	v_cvt_pk_bf16_f32 v22, v12, v13
	v_cvt_pk_bf16_f32 v23, v14, v15
	global_store_dwordx4 v[32:33], v[20:23], off offset:256 sc0 sc1
	v_cvt_pk_bf16_f32 v12, v24, v25
	v_cvt_pk_bf16_f32 v13, v26, v27
	v_cvt_pk_bf16_f32 v14, v16, v17
	v_add_co_u32_e32 v16, vcc, s2, v128
	s_mov_b64 s[56:57], 0x40000
	s_nop 0
	v_addc_co_u32_e32 v17, vcc, 0, v129, vcc
	s_and_b64 vcc, exec, s[38:39]
	v_readlane_b32 s55, v250, 53
	v_cvt_pk_bf16_f32 v15, v18, v19
	global_store_dwordx4 v[16:17], v[12:15], off sc0 sc1
	v_cvt_pk_bf16_f32 v8, v8, v9
	v_cvt_pk_bf16_f32 v9, v10, v11
	v_cvt_pk_bf16_f32 v10, v4, v5
	v_cvt_pk_bf16_f32 v11, v6, v7
	global_store_dwordx4 v[16:17], v[8:11], off offset:256 sc0 sc1
	s_branch .Ljoin_out

.LBB0_1222:
	s_add_u32 s20, s18, 0xfff80080
	s_addc_u32 s21, s19, -1
	s_add_i32 s54, 0, 0x10000
	s_cmp_eq_u32 s53, 28
	s_cselect_b32 s25, s13, s21
	s_cselect_b32 s24, s49, s20
	v_add_u32_e32 v142, s54, v144
	s_cselect_b32 s21, s11, s52
	s_cselect_b32 s20, s50, s51
	s_add_i32 s56, 0, 0x14000
	ds_read_b128 v[148:151], v142
	ds_read_b128 v[152:155], v142 offset:1024
	ds_read_b128 v[156:159], v142 offset:2048
	ds_read_b128 v[160:163], v142 offset:3072
	v_add_u32_e32 v142, s56, v144
	ds_read_b128 v[164:167], v142
	ds_read_b128 v[180:183], v142 offset:1024
	ds_read_b128 v[184:187], v142 offset:2048
	ds_read_b128 v[188:191], v142 offset:3072
	v_lshl_add_u64 v[142:143], s[18:19], 0, v[138:139]
	s_add_i32 m0, s34, 0xc000
	ds_read_b128 v[192:195], v146
	ds_read_b128 v[196:199], v146 offset:1024
	ds_read_b128 v[208:211], v146 offset:2048
	ds_read_b128 v[212:215], v146 offset:3072
	ds_read_b128 v[216:219], v146 offset:4096
	ds_read_b128 v[220:223], v146 offset:5120
	ds_read_b128 v[224:227], v146 offset:6144
	ds_read_b128 v[228:231], v146 offset:7168
	global_load_lds_dwordx4 v[142:143], off
	v_lshl_add_u64 v[142:143], s[18:19], 0, v[140:141]
	s_add_i32 m0, s34, 0xe000
	s_nop 0
	global_load_lds_dwordx4 v[142:143], off
	s_waitcnt vmcnt(8)
	s_waitcnt lgkmcnt(0)
	s_barrier
	s_waitcnt lgkmcnt(0)
	v_mfma_f32_16x16x32_bf16 v[128:131], v[148:151], v[192:195], v[128:131]
	v_mfma_f32_16x16x32_bf16 v[124:127], v[156:159], v[192:195], v[124:127]
	v_mfma_f32_16x16x32_bf16 v[112:115], v[148:151], v[208:211], v[112:115]
	v_mfma_f32_16x16x32_bf16 v[108:111], v[156:159], v[208:211], v[108:111]
	v_mfma_f32_16x16x32_bf16 v[96:99], v[148:151], v[216:219], v[96:99]
	v_mfma_f32_16x16x32_bf16 v[92:95], v[156:159], v[216:219], v[92:95]
	v_mfma_f32_16x16x32_bf16 v[80:83], v[148:151], v[224:227], v[80:83]
	v_mfma_f32_16x16x32_bf16 v[76:79], v[156:159], v[224:227], v[76:79]
	v_mfma_f32_16x16x32_bf16 v[128:131], v[152:155], v[196:199], v[128:131]
	v_mfma_f32_16x16x32_bf16 v[124:127], v[160:163], v[196:199], v[124:127]
	v_mfma_f32_16x16x32_bf16 v[112:115], v[152:155], v[212:215], v[112:115]
	v_mfma_f32_16x16x32_bf16 v[108:111], v[160:163], v[212:215], v[108:111]
	v_mfma_f32_16x16x32_bf16 v[96:99], v[152:155], v[220:223], v[96:99]
	v_mfma_f32_16x16x32_bf16 v[92:95], v[160:163], v[220:223], v[92:95]
	v_mfma_f32_16x16x32_bf16 v[80:83], v[152:155], v[228:231], v[80:83]
	v_mfma_f32_16x16x32_bf16 v[76:79], v[160:163], v[228:231], v[76:79]
	v_mfma_f32_16x16x32_bf16 v[120:123], v[164:167], v[192:195], v[120:123]
	v_mfma_f32_16x16x32_bf16 v[116:119], v[184:187], v[192:195], v[116:119]
	v_mfma_f32_16x16x32_bf16 v[104:107], v[164:167], v[208:211], v[104:107]
	v_mfma_f32_16x16x32_bf16 v[100:103], v[184:187], v[208:211], v[100:103]
	v_mfma_f32_16x16x32_bf16 v[88:91], v[164:167], v[216:219], v[88:91]
	v_mfma_f32_16x16x32_bf16 v[84:87], v[184:187], v[216:219], v[84:87]
	v_mfma_f32_16x16x32_bf16 v[72:75], v[164:167], v[224:227], v[72:75]
	v_mfma_f32_16x16x32_bf16 v[68:71], v[184:187], v[224:227], v[68:71]
	v_mfma_f32_16x16x32_bf16 v[120:123], v[180:183], v[196:199], v[120:123]
	v_mfma_f32_16x16x32_bf16 v[116:119], v[188:191], v[196:199], v[116:119]
	v_mfma_f32_16x16x32_bf16 v[104:107], v[180:183], v[212:215], v[104:107]
	v_mfma_f32_16x16x32_bf16 v[100:103], v[188:191], v[212:215], v[100:103]
	v_mfma_f32_16x16x32_bf16 v[88:91], v[180:183], v[220:223], v[88:91]
	v_mfma_f32_16x16x32_bf16 v[84:87], v[188:191], v[220:223], v[84:87]
	v_mfma_f32_16x16x32_bf16 v[72:75], v[180:183], v[228:231], v[72:75]
	v_mfma_f32_16x16x32_bf16 v[68:71], v[188:191], v[228:231], v[68:71]
	s_barrier
	s_add_i32 s54, s54, s28
	v_lshl_add_u64 v[142:143], s[20:21], 0, v[2:3]
	s_mov_b32 m0, s54
	ds_read_b128 v[192:195], v146 offset:16384
	ds_read_b128 v[196:199], v146 offset:17408
	ds_read_b128 v[208:211], v146 offset:18432
	ds_read_b128 v[212:215], v146 offset:19456
	ds_read_b128 v[216:219], v146 offset:20480
	ds_read_b128 v[220:223], v146 offset:21504
	ds_read_b128 v[224:227], v146 offset:22528
	ds_read_b128 v[228:231], v146 offset:23552
	global_load_lds_dwordx4 v[142:143], off
	s_add_i32 m0, s54, 0x2000
	s_add_u32 s54, s20, 0x80000
	v_lshl_add_u64 v[232:233], s[20:21], 0, v[132:133]
	s_addc_u32 s55, s21, 0
	s_add_i32 s56, s56, s28
	global_load_lds_dwordx4 v[232:233], off
	v_lshl_add_u64 v[234:235], s[54:55], 0, v[2:3]
	s_mov_b32 m0, s56
	v_lshl_add_u64 v[236:237], s[24:25], 0, v[134:135]
	global_load_lds_dwordx4 v[234:235], off
	v_lshl_add_u64 v[234:235], s[54:55], 0, v[132:133]
	s_add_i32 m0, s56, 0x2000
	s_nop 0
	global_load_lds_dwordx4 v[234:235], off
	v_lshl_add_u64 v[234:235], s[24:25], 0, v[136:137]
	s_mov_b32 m0, s34
	s_nop 0
	global_load_lds_dwordx4 v[234:235], off
	s_mov_b32 m0, s35
	s_nop 0
	global_load_lds_dwordx4 v[236:237], off
	s_waitcnt vmcnt(8)
	s_waitcnt lgkmcnt(0)
	s_barrier
	s_waitcnt lgkmcnt(0)
	v_mfma_f32_16x16x32_bf16 v[64:67], v[148:151], v[192:195], v[64:67]
	v_mfma_f32_16x16x32_bf16 v[60:63], v[156:159], v[192:195], v[60:63]
	v_mfma_f32_16x16x32_bf16 v[48:51], v[148:151], v[208:211], v[48:51]
	v_mfma_f32_16x16x32_bf16 v[44:47], v[156:159], v[208:211], v[44:47]
	v_mfma_f32_16x16x32_bf16 v[32:35], v[148:151], v[216:219], v[32:35]
	v_mfma_f32_16x16x32_bf16 v[28:31], v[156:159], v[216:219], v[28:31]
	v_mfma_f32_16x16x32_bf16 v[16:19], v[148:151], v[224:227], v[16:19]
	v_mfma_f32_16x16x32_bf16 v[12:15], v[156:159], v[224:227], v[12:15]
	v_mfma_f32_16x16x32_bf16 v[64:67], v[152:155], v[196:199], v[64:67]
	v_mfma_f32_16x16x32_bf16 v[60:63], v[160:163], v[196:199], v[60:63]
	v_mfma_f32_16x16x32_bf16 v[48:51], v[152:155], v[212:215], v[48:51]
	v_mfma_f32_16x16x32_bf16 v[44:47], v[160:163], v[212:215], v[44:47]
	v_mfma_f32_16x16x32_bf16 v[32:35], v[152:155], v[220:223], v[32:35]
	v_mfma_f32_16x16x32_bf16 v[28:31], v[160:163], v[220:223], v[28:31]
	v_mfma_f32_16x16x32_bf16 v[16:19], v[152:155], v[228:231], v[16:19]
	v_mfma_f32_16x16x32_bf16 v[12:15], v[160:163], v[228:231], v[12:15]
	v_mfma_f32_16x16x32_bf16 v[56:59], v[164:167], v[192:195], v[56:59]
	v_mfma_f32_16x16x32_bf16 v[52:55], v[184:187], v[192:195], v[52:55]
	v_mfma_f32_16x16x32_bf16 v[40:43], v[164:167], v[208:211], v[40:43]
	v_mfma_f32_16x16x32_bf16 v[36:39], v[184:187], v[208:211], v[36:39]
	v_mfma_f32_16x16x32_bf16 v[24:27], v[164:167], v[216:219], v[24:27]
	v_mfma_f32_16x16x32_bf16 v[20:23], v[184:187], v[216:219], v[20:23]
	v_mfma_f32_16x16x32_bf16 v[8:11], v[164:167], v[224:227], v[8:11]
	v_mfma_f32_16x16x32_bf16 v[4:7], v[184:187], v[224:227], v[4:7]
	v_mfma_f32_16x16x32_bf16 v[56:59], v[180:183], v[196:199], v[56:59]
	v_mfma_f32_16x16x32_bf16 v[52:55], v[188:191], v[196:199], v[52:55]
	v_mfma_f32_16x16x32_bf16 v[40:43], v[180:183], v[212:215], v[40:43]
	v_mfma_f32_16x16x32_bf16 v[36:39], v[188:191], v[212:215], v[36:39]
	v_mfma_f32_16x16x32_bf16 v[24:27], v[180:183], v[220:223], v[24:27]
	v_mfma_f32_16x16x32_bf16 v[20:23], v[188:191], v[220:223], v[20:23]
	v_mfma_f32_16x16x32_bf16 v[8:11], v[180:183], v[228:231], v[8:11]
	v_mfma_f32_16x16x32_bf16 v[4:7], v[188:191], v[228:231], v[4:7]
	s_barrier
	s_add_i32 s54, 0, 0x18000
	v_add_u32_e32 v147, s54, v144
	s_add_i32 s55, 0, 0x1c000
	ds_read_b128 v[148:151], v147
	ds_read_b128 v[152:155], v147 offset:1024
	ds_read_b128 v[156:159], v147 offset:2048
	ds_read_b128 v[160:163], v147 offset:3072
	v_add_u32_e32 v147, s55, v144
	ds_read_b128 v[164:167], v147
	ds_read_b128 v[180:183], v147 offset:1024
	ds_read_b128 v[184:187], v147 offset:2048
	ds_read_b128 v[188:191], v147 offset:3072
	s_add_u32 s24, s24, 0x80000
	s_addc_u32 s25, s25, 0
	s_mov_b32 m0, s42
	v_lshl_add_u64 v[238:239], s[24:25], 0, v[136:137]
	ds_read_b128 v[192:195], v146 offset:32768
	ds_read_b128 v[196:199], v146 offset:33792
	ds_read_b128 v[208:211], v146 offset:34816
	ds_read_b128 v[212:215], v146 offset:35840
	ds_read_b128 v[216:219], v146 offset:36864
	ds_read_b128 v[220:223], v146 offset:37888
	ds_read_b128 v[224:227], v146 offset:38912
	ds_read_b128 v[228:231], v146 offset:39936
	global_load_lds_dwordx4 v[238:239], off
	v_lshl_add_u64 v[238:239], s[24:25], 0, v[134:135]
	s_mov_b32 m0, s43
	s_nop 0
	global_load_lds_dwordx4 v[238:239], off
	s_waitcnt vmcnt(8)
	s_waitcnt lgkmcnt(0)
	s_barrier
	s_waitcnt lgkmcnt(0)
	v_mfma_f32_16x16x32_bf16 v[128:131], v[148:151], v[192:195], v[128:131]
	v_mfma_f32_16x16x32_bf16 v[124:127], v[156:159], v[192:195], v[124:127]
	v_mfma_f32_16x16x32_bf16 v[112:115], v[148:151], v[208:211], v[112:115]
	v_mfma_f32_16x16x32_bf16 v[108:111], v[156:159], v[208:211], v[108:111]
	v_mfma_f32_16x16x32_bf16 v[96:99], v[148:151], v[216:219], v[96:99]
	v_mfma_f32_16x16x32_bf16 v[92:95], v[156:159], v[216:219], v[92:95]
	v_mfma_f32_16x16x32_bf16 v[80:83], v[148:151], v[224:227], v[80:83]
	v_mfma_f32_16x16x32_bf16 v[76:79], v[156:159], v[224:227], v[76:79]
	v_mfma_f32_16x16x32_bf16 v[128:131], v[152:155], v[196:199], v[128:131]
	v_mfma_f32_16x16x32_bf16 v[124:127], v[160:163], v[196:199], v[124:127]
	v_mfma_f32_16x16x32_bf16 v[112:115], v[152:155], v[212:215], v[112:115]
	v_mfma_f32_16x16x32_bf16 v[108:111], v[160:163], v[212:215], v[108:111]
	v_mfma_f32_16x16x32_bf16 v[96:99], v[152:155], v[220:223], v[96:99]
	v_mfma_f32_16x16x32_bf16 v[92:95], v[160:163], v[220:223], v[92:95]
	v_mfma_f32_16x16x32_bf16 v[80:83], v[152:155], v[228:231], v[80:83]
	v_mfma_f32_16x16x32_bf16 v[76:79], v[160:163], v[228:231], v[76:79]
	v_mfma_f32_16x16x32_bf16 v[120:123], v[164:167], v[192:195], v[120:123]
	v_mfma_f32_16x16x32_bf16 v[116:119], v[184:187], v[192:195], v[116:119]
	v_mfma_f32_16x16x32_bf16 v[104:107], v[164:167], v[208:211], v[104:107]
	v_mfma_f32_16x16x32_bf16 v[100:103], v[184:187], v[208:211], v[100:103]
	v_mfma_f32_16x16x32_bf16 v[88:91], v[164:167], v[216:219], v[88:91]
	v_mfma_f32_16x16x32_bf16 v[84:87], v[184:187], v[216:219], v[84:87]
	v_mfma_f32_16x16x32_bf16 v[72:75], v[164:167], v[224:227], v[72:75]
	v_mfma_f32_16x16x32_bf16 v[68:71], v[184:187], v[224:227], v[68:71]
	v_mfma_f32_16x16x32_bf16 v[120:123], v[180:183], v[196:199], v[120:123]
	v_mfma_f32_16x16x32_bf16 v[116:119], v[188:191], v[196:199], v[116:119]
	v_mfma_f32_16x16x32_bf16 v[104:107], v[180:183], v[212:215], v[104:107]
	v_mfma_f32_16x16x32_bf16 v[100:103], v[188:191], v[212:215], v[100:103]
	v_mfma_f32_16x16x32_bf16 v[88:91], v[180:183], v[220:223], v[88:91]
	v_mfma_f32_16x16x32_bf16 v[84:87], v[188:191], v[220:223], v[84:87]
	v_mfma_f32_16x16x32_bf16 v[72:75], v[180:183], v[228:231], v[72:75]
	v_mfma_f32_16x16x32_bf16 v[68:71], v[188:191], v[228:231], v[68:71]
	s_barrier
	s_add_i32 s24, s54, s28
	v_lshl_add_u64 v[142:143], v[142:143], 0, s[2:3]
	s_mov_b32 m0, s24
	ds_read_b128 v[192:195], v146 offset:49152
	ds_read_b128 v[196:199], v146 offset:50176
	ds_read_b128 v[208:211], v146 offset:51200
	ds_read_b128 v[212:215], v146 offset:52224
	ds_read_b128 v[216:219], v146 offset:53248
	ds_read_b128 v[220:223], v146 offset:54272
	ds_read_b128 v[224:227], v146 offset:55296
	ds_read_b128 v[228:231], v146 offset:56320
	global_load_lds_dwordx4 v[142:143], off
	s_add_i32 m0, s24, 0x2000
	s_add_u32 s20, s20, 0x80080
	v_lshl_add_u64 v[142:143], v[232:233], 0, s[2:3]
	s_addc_u32 s21, s21, 0
	s_add_i32 s24, s55, s28
	global_load_lds_dwordx4 v[142:143], off
	v_lshl_add_u64 v[142:143], s[20:21], 0, v[2:3]
	s_mov_b32 m0, s24
	s_nop 0
	global_load_lds_dwordx4 v[142:143], off
	v_lshl_add_u64 v[142:143], s[20:21], 0, v[132:133]
	s_add_i32 m0, s24, 0x2000
	s_nop 0
	global_load_lds_dwordx4 v[142:143], off
	v_lshl_add_u64 v[142:143], v[234:235], 0, s[2:3]
	s_mov_b32 m0, s44
	s_nop 0
	global_load_lds_dwordx4 v[142:143], off
	v_lshl_add_u64 v[142:143], v[236:237], 0, s[2:3]
	s_mov_b32 m0, s45
	s_nop 0
	global_load_lds_dwordx4 v[142:143], off
	s_waitcnt vmcnt(8)
	s_waitcnt lgkmcnt(0)
	s_barrier
	s_waitcnt lgkmcnt(0)
	v_mfma_f32_16x16x32_bf16 v[64:67], v[148:151], v[192:195], v[64:67]
	v_mfma_f32_16x16x32_bf16 v[60:63], v[156:159], v[192:195], v[60:63]
	v_mfma_f32_16x16x32_bf16 v[48:51], v[148:151], v[208:211], v[48:51]
	v_mfma_f32_16x16x32_bf16 v[44:47], v[156:159], v[208:211], v[44:47]
	v_mfma_f32_16x16x32_bf16 v[32:35], v[148:151], v[216:219], v[32:35]
	v_mfma_f32_16x16x32_bf16 v[28:31], v[156:159], v[216:219], v[28:31]
	v_mfma_f32_16x16x32_bf16 v[16:19], v[148:151], v[224:227], v[16:19]
	v_mfma_f32_16x16x32_bf16 v[12:15], v[156:159], v[224:227], v[12:15]
	v_mfma_f32_16x16x32_bf16 v[64:67], v[152:155], v[196:199], v[64:67]
	v_mfma_f32_16x16x32_bf16 v[60:63], v[160:163], v[196:199], v[60:63]
	v_mfma_f32_16x16x32_bf16 v[48:51], v[152:155], v[212:215], v[48:51]
	v_mfma_f32_16x16x32_bf16 v[44:47], v[160:163], v[212:215], v[44:47]
	v_mfma_f32_16x16x32_bf16 v[32:35], v[152:155], v[220:223], v[32:35]
	v_mfma_f32_16x16x32_bf16 v[28:31], v[160:163], v[220:223], v[28:31]
	v_mfma_f32_16x16x32_bf16 v[16:19], v[152:155], v[228:231], v[16:19]
	v_mfma_f32_16x16x32_bf16 v[12:15], v[160:163], v[228:231], v[12:15]
	v_mfma_f32_16x16x32_bf16 v[56:59], v[164:167], v[192:195], v[56:59]
	v_mfma_f32_16x16x32_bf16 v[52:55], v[184:187], v[192:195], v[52:55]
	v_mfma_f32_16x16x32_bf16 v[40:43], v[164:167], v[208:211], v[40:43]
	v_mfma_f32_16x16x32_bf16 v[36:39], v[184:187], v[208:211], v[36:39]
	v_mfma_f32_16x16x32_bf16 v[24:27], v[164:167], v[216:219], v[24:27]
	v_mfma_f32_16x16x32_bf16 v[20:23], v[184:187], v[216:219], v[20:23]
	v_mfma_f32_16x16x32_bf16 v[8:11], v[164:167], v[224:227], v[8:11]
	v_mfma_f32_16x16x32_bf16 v[4:7], v[184:187], v[224:227], v[4:7]
	v_mfma_f32_16x16x32_bf16 v[56:59], v[180:183], v[196:199], v[56:59]
	v_mfma_f32_16x16x32_bf16 v[52:55], v[188:191], v[196:199], v[52:55]
	v_mfma_f32_16x16x32_bf16 v[40:43], v[180:183], v[212:215], v[40:43]
	v_mfma_f32_16x16x32_bf16 v[36:39], v[188:191], v[212:215], v[36:39]
	v_mfma_f32_16x16x32_bf16 v[24:27], v[180:183], v[220:223], v[24:27]
	v_mfma_f32_16x16x32_bf16 v[20:23], v[188:191], v[220:223], v[20:23]
	v_mfma_f32_16x16x32_bf16 v[8:11], v[180:183], v[228:231], v[8:11]
	v_mfma_f32_16x16x32_bf16 v[4:7], v[188:191], v[228:231], v[4:7]
	s_barrier
	s_add_i32 s53, s53, 2
	s_add_u32 s18, s18, 0x100
	s_addc_u32 s19, s19, 0
	s_add_u32 s51, s51, 0x100
	s_addc_u32 s52, s52, 0
	s_cmp_gt_u32 s53, 29
	s_cbranch_scc0 .LBB0_1222
	s_and_b64 vcc, exec, s[8:9]
	s_cbranch_vccz .LBB0_1225
	s_barrier
.LBB0_1225:
	s_and_b64 vcc, exec, s[40:41]
	s_cbranch_vccz .Llast_ff1
	v_max_f32_e32 v124, v124, v124
	v_lshl_add_u32 v148, s48, 8, v1
	v_max_f32_e32 v124, 0, v124
	v_max_f32_e32 v125, v125, v125
	v_max_f32_e32 v126, v126, v126
	v_lshl_or_b32 v142, s47, 8, v145
	v_ashrrev_i32_e32 v149, 31, v148
	v_readlane_b32 s2, v246, 29
	v_mul_f32_e32 v147, v124, v124
	v_max_f32_e32 v124, v129, v129
	v_max_f32_e32 v125, 0, v125
	v_max_f32_e32 v126, 0, v126
	v_ashrrev_i32_e32 v143, 31, v142
	v_lshlrev_b64 v[150:151], 14, v[148:149]
	v_readlane_b32 s3, v246, 30
	v_max_f32_e32 v128, v128, v128
	v_max_f32_e32 v124, 0, v124
	v_mul_f32_e32 v129, v125, v125
	v_max_f32_e32 v125, v130, v130
	v_mul_f32_e32 v130, v126, v126
	v_max_f32_e32 v126, v131, v131
	v_max_f32_e32 v127, v127, v127
	v_lshl_add_u64 v[150:151], s[2:3], 0, v[150:151]
	v_lshlrev_b64 v[152:153], 1, v[142:143]
	v_max_f32_e32 v128, 0, v128
	v_mul_f32_e32 v124, v124, v124
	v_max_f32_e32 v125, 0, v125
	v_max_f32_e32 v126, 0, v126
	v_max_f32_e32 v127, 0, v127
	v_max_f32_e32 v116, v116, v116
	v_lshl_add_u64 v[142:143], v[150:151], 0, v[152:153]
	v_mul_f32_e32 v128, v128, v128
	v_mul_f32_e32 v125, v125, v125
	v_mul_f32_e32 v126, v126, v126
	v_mul_f32_e32 v127, v127, v127
	v_cvt_pk_bf16_f32 v124, v128, v124
	v_max_f32_e32 v116, 0, v116
	v_max_f32_e32 v117, v117, v117
	v_max_f32_e32 v118, v118, v118
	v_cvt_pk_bf16_f32 v125, v125, v126
	v_cvt_pk_bf16_f32 v126, v147, v129
	v_cvt_pk_bf16_f32 v127, v130, v127
	global_store_dwordx4 v[142:143], v[124:127], off
	v_max_f32_e32 v117, 0, v117
	v_max_f32_e32 v118, 0, v118
	v_mul_f32_e32 v124, v116, v116
	v_max_f32_e32 v116, v121, v121
	v_max_f32_e32 v120, v120, v120
	v_max_f32_e32 v116, 0, v116
	v_mul_f32_e32 v121, v117, v117
	v_max_f32_e32 v117, v122, v122
	v_mul_f32_e32 v122, v118, v118
	v_max_f32_e32 v118, v123, v123
	v_max_f32_e32 v119, v119, v119
	v_max_f32_e32 v120, 0, v120
	v_mul_f32_e32 v116, v116, v116
	v_max_f32_e32 v117, 0, v117
	v_max_f32_e32 v118, 0, v118
	v_max_f32_e32 v119, 0, v119
	v_mul_f32_e32 v120, v120, v120
	v_mul_f32_e32 v117, v117, v117
	v_mul_f32_e32 v118, v118, v118
	v_mul_f32_e32 v119, v119, v119
	v_cvt_pk_bf16_f32 v116, v120, v116
	v_max_f32_e32 v108, v108, v108
	v_cvt_pk_bf16_f32 v117, v117, v118
	v_cvt_pk_bf16_f32 v118, v124, v121
	v_cvt_pk_bf16_f32 v119, v122, v119
	global_store_dwordx4 v[142:143], v[116:119], off offset:256
	v_max_f32_e32 v108, 0, v108
	v_max_f32_e32 v109, v109, v109
	v_or_b32_e32 v116, 16, v148
	v_max_f32_e32 v110, v110, v110
	v_ashrrev_i32_e32 v117, 31, v116
	v_mul_f32_e32 v118, v108, v108
	v_max_f32_e32 v108, v113, v113
	v_max_f32_e32 v109, 0, v109
	v_max_f32_e32 v110, 0, v110
	v_lshlrev_b64 v[116:117], 14, v[116:117]
	v_max_f32_e32 v112, v112, v112
	v_max_f32_e32 v108, 0, v108
	v_mul_f32_e32 v113, v109, v109
	v_max_f32_e32 v109, v114, v114
	v_mul_f32_e32 v114, v110, v110
	v_max_f32_e32 v110, v115, v115
	v_max_f32_e32 v111, v111, v111
	v_lshl_add_u64 v[116:117], s[2:3], 0, v[116:117]
	v_max_f32_e32 v112, 0, v112
	v_mul_f32_e32 v108, v108, v108
	v_max_f32_e32 v109, 0, v109
	v_max_f32_e32 v110, 0, v110
	v_max_f32_e32 v111, 0, v111
	v_max_f32_e32 v100, v100, v100
	v_lshl_add_u64 v[116:117], v[116:117], 0, v[152:153]
	v_mul_f32_e32 v112, v112, v112
	v_mul_f32_e32 v109, v109, v109
	v_mul_f32_e32 v110, v110, v110
	v_mul_f32_e32 v111, v111, v111
	v_cvt_pk_bf16_f32 v108, v112, v108
	v_max_f32_e32 v100, 0, v100
	v_max_f32_e32 v101, v101, v101
	v_max_f32_e32 v102, v102, v102
	v_cvt_pk_bf16_f32 v109, v109, v110
	v_cvt_pk_bf16_f32 v110, v118, v113
	v_cvt_pk_bf16_f32 v111, v114, v111
	global_store_dwordx4 v[116:117], v[108:111], off
	v_max_f32_e32 v101, 0, v101
	v_max_f32_e32 v102, 0, v102
	v_mul_f32_e32 v108, v100, v100
	v_max_f32_e32 v100, v105, v105
	v_max_f32_e32 v104, v104, v104
	v_max_f32_e32 v100, 0, v100
	v_mul_f32_e32 v105, v101, v101
	v_max_f32_e32 v101, v106, v106
	v_mul_f32_e32 v106, v102, v102
	v_max_f32_e32 v102, v107, v107
	v_max_f32_e32 v103, v103, v103
	v_max_f32_e32 v104, 0, v104
	v_mul_f32_e32 v100, v100, v100
	v_max_f32_e32 v101, 0, v101
	v_max_f32_e32 v102, 0, v102
	v_max_f32_e32 v103, 0, v103
	v_mul_f32_e32 v104, v104, v104
	v_mul_f32_e32 v101, v101, v101
	v_mul_f32_e32 v102, v102, v102
	v_mul_f32_e32 v103, v103, v103
	v_cvt_pk_bf16_f32 v100, v104, v100
	v_max_f32_e32 v92, v92, v92
	v_cvt_pk_bf16_f32 v101, v101, v102
	v_cvt_pk_bf16_f32 v102, v108, v105
	v_cvt_pk_bf16_f32 v103, v106, v103
	global_store_dwordx4 v[116:117], v[100:103], off offset:256
	v_max_f32_e32 v92, 0, v92
	v_max_f32_e32 v93, v93, v93
	v_or_b32_e32 v100, 32, v148
	v_max_f32_e32 v94, v94, v94
	v_ashrrev_i32_e32 v101, 31, v100
	v_mul_f32_e32 v102, v92, v92
	v_max_f32_e32 v92, v97, v97
	v_max_f32_e32 v93, 0, v93
	v_max_f32_e32 v94, 0, v94
	v_lshlrev_b64 v[100:101], 14, v[100:101]
	v_max_f32_e32 v96, v96, v96
	v_max_f32_e32 v92, 0, v92
	v_mul_f32_e32 v97, v93, v93
	v_max_f32_e32 v93, v98, v98
	v_mul_f32_e32 v98, v94, v94
	v_max_f32_e32 v94, v99, v99
	v_max_f32_e32 v95, v95, v95
	v_lshl_add_u64 v[100:101], s[2:3], 0, v[100:101]
	v_max_f32_e32 v96, 0, v96
	v_mul_f32_e32 v92, v92, v92
	v_max_f32_e32 v93, 0, v93
	v_max_f32_e32 v94, 0, v94
	v_max_f32_e32 v95, 0, v95
	v_max_f32_e32 v84, v84, v84
	v_lshl_add_u64 v[100:101], v[100:101], 0, v[152:153]
	v_mul_f32_e32 v96, v96, v96
	v_mul_f32_e32 v93, v93, v93
	v_mul_f32_e32 v94, v94, v94
	v_mul_f32_e32 v95, v95, v95
	v_cvt_pk_bf16_f32 v92, v96, v92
	v_max_f32_e32 v84, 0, v84
	v_max_f32_e32 v85, v85, v85
	v_max_f32_e32 v86, v86, v86
	v_cvt_pk_bf16_f32 v93, v93, v94
	v_cvt_pk_bf16_f32 v94, v102, v97
	v_cvt_pk_bf16_f32 v95, v98, v95
	global_store_dwordx4 v[100:101], v[92:95], off
	v_max_f32_e32 v85, 0, v85
	v_max_f32_e32 v86, 0, v86
	v_mul_f32_e32 v92, v84, v84
	v_max_f32_e32 v84, v89, v89
	v_max_f32_e32 v88, v88, v88
	v_max_f32_e32 v84, 0, v84
	v_mul_f32_e32 v89, v85, v85
	v_max_f32_e32 v85, v90, v90
	v_mul_f32_e32 v90, v86, v86
	v_max_f32_e32 v86, v91, v91
	v_max_f32_e32 v87, v87, v87
	v_max_f32_e32 v88, 0, v88
	v_mul_f32_e32 v84, v84, v84
	v_max_f32_e32 v85, 0, v85
	v_max_f32_e32 v86, 0, v86
	v_max_f32_e32 v87, 0, v87
	v_mul_f32_e32 v88, v88, v88
	v_mul_f32_e32 v85, v85, v85
	v_mul_f32_e32 v86, v86, v86
	v_mul_f32_e32 v87, v87, v87
	v_cvt_pk_bf16_f32 v84, v88, v84
	v_max_f32_e32 v76, v76, v76
	v_cvt_pk_bf16_f32 v85, v85, v86
	v_cvt_pk_bf16_f32 v86, v92, v89
	v_cvt_pk_bf16_f32 v87, v90, v87
	global_store_dwordx4 v[100:101], v[84:87], off offset:256
	v_max_f32_e32 v76, 0, v76
	v_max_f32_e32 v77, v77, v77
	v_or_b32_e32 v84, 48, v148
	v_max_f32_e32 v78, v78, v78
	v_ashrrev_i32_e32 v85, 31, v84
	v_mul_f32_e32 v86, v76, v76
	v_max_f32_e32 v76, v81, v81
	v_max_f32_e32 v77, 0, v77
	v_max_f32_e32 v78, 0, v78
	v_lshlrev_b64 v[84:85], 14, v[84:85]
	v_max_f32_e32 v80, v80, v80
	v_max_f32_e32 v76, 0, v76
	v_mul_f32_e32 v81, v77, v77
	v_max_f32_e32 v77, v82, v82
	v_mul_f32_e32 v82, v78, v78
	v_max_f32_e32 v78, v83, v83
	v_max_f32_e32 v79, v79, v79
	v_lshl_add_u64 v[84:85], s[2:3], 0, v[84:85]
	v_max_f32_e32 v80, 0, v80
	v_mul_f32_e32 v76, v76, v76
	v_max_f32_e32 v77, 0, v77
	v_max_f32_e32 v78, 0, v78
	v_max_f32_e32 v79, 0, v79
	v_max_f32_e32 v68, v68, v68
	v_max_f32_e32 v69, v69, v69
	v_max_f32_e32 v70, v70, v70
	v_lshl_add_u64 v[84:85], v[84:85], 0, v[152:153]
	v_mul_f32_e32 v80, v80, v80
	v_mul_f32_e32 v77, v77, v77
	v_mul_f32_e32 v78, v78, v78
	v_mul_f32_e32 v79, v79, v79
	v_cvt_pk_bf16_f32 v76, v80, v76
	v_max_f32_e32 v68, 0, v68
	v_max_f32_e32 v69, 0, v69
	v_max_f32_e32 v70, 0, v70
	v_cvt_pk_bf16_f32 v77, v77, v78
	v_cvt_pk_bf16_f32 v78, v86, v81
	v_cvt_pk_bf16_f32 v79, v82, v79
	global_store_dwordx4 v[84:85], v[76:79], off
	v_max_f32_e32 v72, v72, v72
	v_max_f32_e32 v71, v71, v71
	v_mul_f32_e32 v76, v68, v68
	v_max_f32_e32 v68, v73, v73
	v_mul_f32_e32 v73, v69, v69
	v_max_f32_e32 v69, v74, v74
	v_mul_f32_e32 v74, v70, v70
	v_max_f32_e32 v70, v75, v75
	v_max_f32_e32 v68, 0, v68
	v_max_f32_e32 v69, 0, v69
	v_max_f32_e32 v70, 0, v70
	v_max_f32_e32 v72, 0, v72
	v_mul_f32_e32 v68, v68, v68
	v_mul_f32_e32 v69, v69, v69
	v_max_f32_e32 v71, 0, v71
	v_mul_f32_e32 v70, v70, v70
	v_max_f32_e32 v60, v60, v60
	v_mul_f32_e32 v72, v72, v72
	v_mul_f32_e32 v71, v71, v71
	v_cvt_pk_bf16_f32 v68, v72, v68
	v_cvt_pk_bf16_f32 v69, v69, v70
	v_cvt_pk_bf16_f32 v70, v76, v73
	v_max_f32_e32 v60, 0, v60
	v_max_f32_e32 v61, v61, v61
	v_max_f32_e32 v62, v62, v62
	v_cvt_pk_bf16_f32 v71, v74, v71
	global_store_dwordx4 v[84:85], v[68:71], off offset:256
	v_max_f32_e32 v64, v64, v64
	v_max_f32_e32 v61, 0, v61
	v_mul_f32_e32 v70, v60, v60
	v_max_f32_e32 v60, v65, v65
	v_max_f32_e32 v62, 0, v62
	v_max_f32_e32 v64, 0, v64
	v_max_f32_e32 v60, 0, v60
	v_mul_f32_e32 v65, v61, v61
	v_max_f32_e32 v61, v66, v66
	v_mul_f32_e32 v66, v62, v62
	v_max_f32_e32 v62, v67, v67
	v_mul_f32_e32 v64, v64, v64
	v_mul_f32_e32 v60, v60, v60
	v_max_f32_e32 v61, 0, v61
	v_max_f32_e32 v62, 0, v62
	v_max_f32_e32 v63, v63, v63
	s_mov_b32 s11, 0x200000
	v_mul_f32_e32 v61, v61, v61
	v_max_f32_e32 v63, 0, v63
	v_mul_f32_e32 v62, v62, v62
	v_cvt_pk_bf16_f32 v60, v64, v60
	v_add_co_u32_e32 v64, vcc, s11, v142
	v_max_f32_e32 v52, v52, v52
	v_max_f32_e32 v53, v53, v53
	v_max_f32_e32 v54, v54, v54
	v_mul_f32_e32 v63, v63, v63
	v_cvt_pk_bf16_f32 v61, v61, v62
	v_cvt_pk_bf16_f32 v62, v70, v65
	v_addc_co_u32_e32 v65, vcc, 0, v143, vcc
	v_max_f32_e32 v52, 0, v52
	v_max_f32_e32 v53, 0, v53
	v_max_f32_e32 v54, 0, v54
	v_cvt_pk_bf16_f32 v63, v66, v63
	global_store_dwordx4 v[64:65], v[60:63], off
	v_max_f32_e32 v56, v56, v56
	v_max_f32_e32 v55, v55, v55
	v_mul_f32_e32 v60, v52, v52
	v_max_f32_e32 v52, v57, v57
	v_mul_f32_e32 v57, v53, v53
	v_max_f32_e32 v53, v58, v58
	v_mul_f32_e32 v58, v54, v54
	v_max_f32_e32 v54, v59, v59
	v_max_f32_e32 v52, 0, v52
	v_max_f32_e32 v53, 0, v53
	v_max_f32_e32 v54, 0, v54
	s_mov_b64 s[18:19], 0x200000
	v_max_f32_e32 v56, 0, v56
	v_mul_f32_e32 v52, v52, v52
	v_mul_f32_e32 v53, v53, v53
	v_max_f32_e32 v55, 0, v55
	v_mul_f32_e32 v54, v54, v54
	v_max_f32_e32 v44, v44, v44
	v_lshl_add_u64 v[68:69], v[142:143], 0, s[18:19]
	v_mul_f32_e32 v56, v56, v56
	v_mul_f32_e32 v55, v55, v55
	v_cvt_pk_bf16_f32 v52, v56, v52
	v_cvt_pk_bf16_f32 v53, v53, v54
	v_cvt_pk_bf16_f32 v54, v60, v57
	v_max_f32_e32 v44, 0, v44
	v_max_f32_e32 v45, v45, v45
	v_max_f32_e32 v46, v46, v46
	v_cvt_pk_bf16_f32 v55, v58, v55
	global_store_dwordx4 v[68:69], v[52:55], off offset:256
	v_max_f32_e32 v48, v48, v48
	v_max_f32_e32 v45, 0, v45
	v_mul_f32_e32 v54, v44, v44
	v_max_f32_e32 v44, v49, v49
	v_max_f32_e32 v46, 0, v46
	v_max_f32_e32 v48, 0, v48
	v_max_f32_e32 v44, 0, v44
	v_mul_f32_e32 v49, v45, v45
	v_max_f32_e32 v45, v50, v50
	v_mul_f32_e32 v50, v46, v46
	v_max_f32_e32 v46, v51, v51
	v_mul_f32_e32 v48, v48, v48
	v_mul_f32_e32 v44, v44, v44
	v_max_f32_e32 v45, 0, v45
	v_max_f32_e32 v46, 0, v46
	v_max_f32_e32 v47, v47, v47
	s_mov_b32 s11, 0x240000
	v_mul_f32_e32 v45, v45, v45
	v_max_f32_e32 v47, 0, v47
	v_mul_f32_e32 v46, v46, v46
	v_cvt_pk_bf16_f32 v44, v48, v44
	v_add_co_u32_e32 v48, vcc, s11, v142
	v_max_f32_e32 v36, v36, v36
	v_max_f32_e32 v37, v37, v37
	v_max_f32_e32 v38, v38, v38
	v_mul_f32_e32 v47, v47, v47
	v_cvt_pk_bf16_f32 v45, v45, v46
	v_cvt_pk_bf16_f32 v46, v54, v49
	v_addc_co_u32_e32 v49, vcc, 0, v143, vcc
	v_max_f32_e32 v36, 0, v36
	v_max_f32_e32 v37, 0, v37
	v_max_f32_e32 v38, 0, v38
	v_cvt_pk_bf16_f32 v47, v50, v47
	global_store_dwordx4 v[48:49], v[44:47], off
	v_max_f32_e32 v40, v40, v40
	v_max_f32_e32 v39, v39, v39
	v_mul_f32_e32 v44, v36, v36
	v_max_f32_e32 v36, v41, v41
	v_mul_f32_e32 v41, v37, v37
	v_max_f32_e32 v37, v42, v42
	v_mul_f32_e32 v42, v38, v38
	v_max_f32_e32 v38, v43, v43
	v_max_f32_e32 v36, 0, v36
	v_max_f32_e32 v37, 0, v37
	v_max_f32_e32 v38, 0, v38
	s_mov_b64 s[18:19], 0x240000
	v_max_f32_e32 v40, 0, v40
	v_mul_f32_e32 v36, v36, v36
	v_mul_f32_e32 v37, v37, v37
	v_max_f32_e32 v39, 0, v39
	v_mul_f32_e32 v38, v38, v38
	v_max_f32_e32 v28, v28, v28
	v_lshl_add_u64 v[52:53], v[142:143], 0, s[18:19]
	v_mul_f32_e32 v40, v40, v40
	v_mul_f32_e32 v39, v39, v39
	v_cvt_pk_bf16_f32 v36, v40, v36
	v_cvt_pk_bf16_f32 v37, v37, v38
	v_cvt_pk_bf16_f32 v38, v44, v41
	v_max_f32_e32 v28, 0, v28
	v_max_f32_e32 v29, v29, v29
	v_max_f32_e32 v30, v30, v30
	v_cvt_pk_bf16_f32 v39, v42, v39
	global_store_dwordx4 v[52:53], v[36:39], off offset:256
	v_max_f32_e32 v32, v32, v32
	v_max_f32_e32 v29, 0, v29
	v_mul_f32_e32 v38, v28, v28
	v_max_f32_e32 v28, v33, v33
	v_max_f32_e32 v30, 0, v30
	v_max_f32_e32 v32, 0, v32
	v_max_f32_e32 v28, 0, v28
	v_mul_f32_e32 v33, v29, v29
	v_max_f32_e32 v29, v34, v34
	v_mul_f32_e32 v34, v30, v30
	v_max_f32_e32 v30, v35, v35
	v_mul_f32_e32 v32, v32, v32
	v_mul_f32_e32 v28, v28, v28
	v_max_f32_e32 v29, 0, v29
	v_max_f32_e32 v30, 0, v30
	v_max_f32_e32 v31, v31, v31
	s_mov_b32 s11, 0x280000
	v_mul_f32_e32 v29, v29, v29
	v_max_f32_e32 v31, 0, v31
	v_mul_f32_e32 v30, v30, v30
	v_cvt_pk_bf16_f32 v28, v32, v28
	v_add_co_u32_e32 v32, vcc, s11, v142
	v_max_f32_e32 v20, v20, v20
	v_max_f32_e32 v21, v21, v21
	v_max_f32_e32 v22, v22, v22
	v_mul_f32_e32 v31, v31, v31
	v_cvt_pk_bf16_f32 v29, v29, v30
	v_cvt_pk_bf16_f32 v30, v38, v33
	v_addc_co_u32_e32 v33, vcc, 0, v143, vcc
	v_max_f32_e32 v20, 0, v20
	v_max_f32_e32 v21, 0, v21
	v_max_f32_e32 v22, 0, v22
	v_cvt_pk_bf16_f32 v31, v34, v31
	global_store_dwordx4 v[32:33], v[28:31], off
	v_max_f32_e32 v24, v24, v24
	v_max_f32_e32 v23, v23, v23
	v_mul_f32_e32 v28, v20, v20
	v_max_f32_e32 v20, v25, v25
	v_mul_f32_e32 v25, v21, v21
	v_max_f32_e32 v21, v26, v26
	v_mul_f32_e32 v26, v22, v22
	v_max_f32_e32 v22, v27, v27
	v_max_f32_e32 v20, 0, v20
	v_max_f32_e32 v21, 0, v21
	v_max_f32_e32 v22, 0, v22
	s_mov_b64 s[18:19], 0x280000
	v_max_f32_e32 v24, 0, v24
	v_mul_f32_e32 v20, v20, v20
	v_mul_f32_e32 v21, v21, v21
	v_max_f32_e32 v23, 0, v23
	v_mul_f32_e32 v22, v22, v22
	v_max_f32_e32 v12, v12, v12
	v_lshl_add_u64 v[36:37], v[142:143], 0, s[18:19]
	v_mul_f32_e32 v24, v24, v24
	v_mul_f32_e32 v23, v23, v23
	v_cvt_pk_bf16_f32 v20, v24, v20
	v_cvt_pk_bf16_f32 v21, v21, v22
	v_cvt_pk_bf16_f32 v22, v28, v25
	v_max_f32_e32 v12, 0, v12
	v_max_f32_e32 v13, v13, v13
	v_max_f32_e32 v14, v14, v14
	v_cvt_pk_bf16_f32 v23, v26, v23
	global_store_dwordx4 v[36:37], v[20:23], off offset:256
	v_max_f32_e32 v16, v16, v16
	v_max_f32_e32 v13, 0, v13
	v_mul_f32_e32 v22, v12, v12
	v_max_f32_e32 v12, v17, v17
	v_max_f32_e32 v14, 0, v14
	v_max_f32_e32 v16, 0, v16
	v_max_f32_e32 v12, 0, v12
	v_mul_f32_e32 v17, v13, v13
	v_max_f32_e32 v13, v18, v18
	v_mul_f32_e32 v18, v14, v14
	v_max_f32_e32 v14, v19, v19
	v_mul_f32_e32 v16, v16, v16
	v_mul_f32_e32 v12, v12, v12
	v_max_f32_e32 v13, 0, v13
	v_max_f32_e32 v14, 0, v14
	v_max_f32_e32 v15, v15, v15
	s_mov_b32 s11, 0x2c0000
	v_mul_f32_e32 v13, v13, v13
	v_max_f32_e32 v15, 0, v15
	v_mul_f32_e32 v14, v14, v14
	v_cvt_pk_bf16_f32 v12, v16, v12
	v_add_co_u32_e32 v16, vcc, s11, v142
	v_max_f32_e32 v4, v4, v4
	v_max_f32_e32 v5, v5, v5
	v_max_f32_e32 v6, v6, v6
	v_mul_f32_e32 v15, v15, v15
	v_cvt_pk_bf16_f32 v13, v13, v14
	v_cvt_pk_bf16_f32 v14, v22, v17
	v_addc_co_u32_e32 v17, vcc, 0, v143, vcc
	v_max_f32_e32 v4, 0, v4
	v_max_f32_e32 v5, 0, v5
	v_max_f32_e32 v6, 0, v6
	v_cvt_pk_bf16_f32 v15, v18, v15
	global_store_dwordx4 v[16:17], v[12:15], off
	v_max_f32_e32 v7, v7, v7
	s_mov_b64 s[18:19], 0x2c0000
	v_mul_f32_e32 v12, v4, v4
	v_max_f32_e32 v4, v9, v9
	v_mul_f32_e32 v9, v5, v5
	v_max_f32_e32 v5, v10, v10
	v_mul_f32_e32 v10, v6, v6
	v_max_f32_e32 v6, v11, v11
	v_max_f32_e32 v8, v8, v8
	v_max_f32_e32 v4, 0, v4
	v_max_f32_e32 v5, 0, v5
	v_max_f32_e32 v6, 0, v6
	v_max_f32_e32 v7, 0, v7
	v_readlane_b32 s54, v250, 52
	v_lshl_add_u64 v[20:21], v[142:143], 0, s[18:19]
	v_max_f32_e32 v8, 0, v8
	v_mul_f32_e32 v4, v4, v4
	v_mul_f32_e32 v5, v5, v5
	v_mul_f32_e32 v6, v6, v6
	v_mul_f32_e32 v7, v7, v7
	s_andn2_b64 vcc, exec, s[40:41]
	s_mov_b64 s[18:19], -1
	s_mov_b64 s[56:57], 0x40000
	v_readlane_b32 s55, v250, 53
	v_mul_f32_e32 v8, v8, v8
	v_cvt_pk_bf16_f32 v4, v8, v4
	v_cvt_pk_bf16_f32 v5, v5, v6
	v_cvt_pk_bf16_f32 v6, v12, v9
	v_cvt_pk_bf16_f32 v7, v10, v7
	global_store_dwordx4 v[20:21], v[4:7], off offset:256
.Ljoin_ff1:
	s_cbranch_vccnz .LBB0_1218
	s_andn2_b64 vcc, exec, s[6:7]
	s_cbranch_vccnz .LBB0_1217
	s_barrier
	s_branch .LBB0_1217
.Llast_ff1:
	v_max_f32_e32 v124, v124, v124
	v_lshl_add_u32 v148, s48, 8, v1
	v_max_f32_e32 v124, 0, v124
	v_max_f32_e32 v125, v125, v125
	v_max_f32_e32 v126, v126, v126
	v_lshl_or_b32 v142, s47, 8, v145
	v_ashrrev_i32_e32 v149, 31, v148
	v_readlane_b32 s2, v246, 29
	v_mul_f32_e32 v147, v124, v124
	v_max_f32_e32 v124, v129, v129
	v_max_f32_e32 v125, 0, v125
	v_max_f32_e32 v126, 0, v126
	v_ashrrev_i32_e32 v143, 31, v142
	v_lshlrev_b64 v[150:151], 14, v[148:149]
	v_readlane_b32 s3, v246, 30
	v_max_f32_e32 v128, v128, v128
	v_max_f32_e32 v124, 0, v124
	v_mul_f32_e32 v129, v125, v125
	v_max_f32_e32 v125, v130, v130
	v_mul_f32_e32 v130, v126, v126
	v_max_f32_e32 v126, v131, v131
	v_max_f32_e32 v127, v127, v127
	v_lshl_add_u64 v[150:151], s[2:3], 0, v[150:151]
	v_lshlrev_b64 v[152:153], 1, v[142:143]
	v_max_f32_e32 v128, 0, v128
	v_mul_f32_e32 v124, v124, v124
	v_max_f32_e32 v125, 0, v125
	v_max_f32_e32 v126, 0, v126
	v_max_f32_e32 v127, 0, v127
	v_max_f32_e32 v116, v116, v116
	v_lshl_add_u64 v[142:143], v[150:151], 0, v[152:153]
	v_mul_f32_e32 v128, v128, v128
	v_mul_f32_e32 v125, v125, v125
	v_mul_f32_e32 v126, v126, v126
	v_mul_f32_e32 v127, v127, v127
	v_cvt_pk_bf16_f32 v124, v128, v124
	v_max_f32_e32 v116, 0, v116
	v_max_f32_e32 v117, v117, v117
	v_max_f32_e32 v118, v118, v118
	v_cvt_pk_bf16_f32 v125, v125, v126
	v_cvt_pk_bf16_f32 v126, v147, v129
	v_cvt_pk_bf16_f32 v127, v130, v127
	global_store_dwordx4 v[142:143], v[124:127], off sc0 sc1
	v_max_f32_e32 v117, 0, v117
	v_max_f32_e32 v118, 0, v118
	v_mul_f32_e32 v124, v116, v116
	v_max_f32_e32 v116, v121, v121
	v_max_f32_e32 v120, v120, v120
	v_max_f32_e32 v116, 0, v116
	v_mul_f32_e32 v121, v117, v117
	v_max_f32_e32 v117, v122, v122
	v_mul_f32_e32 v122, v118, v118
	v_max_f32_e32 v118, v123, v123
	v_max_f32_e32 v119, v119, v119
	v_max_f32_e32 v120, 0, v120
	v_mul_f32_e32 v116, v116, v116
	v_max_f32_e32 v117, 0, v117
	v_max_f32_e32 v118, 0, v118
	v_max_f32_e32 v119, 0, v119
	v_mul_f32_e32 v120, v120, v120
	v_mul_f32_e32 v117, v117, v117
	v_mul_f32_e32 v118, v118, v118
	v_mul_f32_e32 v119, v119, v119
	v_cvt_pk_bf16_f32 v116, v120, v116
	v_max_f32_e32 v108, v108, v108
	v_cvt_pk_bf16_f32 v117, v117, v118
	v_cvt_pk_bf16_f32 v118, v124, v121
	v_cvt_pk_bf16_f32 v119, v122, v119
	global_store_dwordx4 v[142:143], v[116:119], off offset:256 sc0 sc1
	v_max_f32_e32 v108, 0, v108
	v_max_f32_e32 v109, v109, v109
	v_or_b32_e32 v116, 16, v148
	v_max_f32_e32 v110, v110, v110
	v_ashrrev_i32_e32 v117, 31, v116
	v_mul_f32_e32 v118, v108, v108
	v_max_f32_e32 v108, v113, v113
	v_max_f32_e32 v109, 0, v109
	v_max_f32_e32 v110, 0, v110
	v_lshlrev_b64 v[116:117], 14, v[116:117]
	v_max_f32_e32 v112, v112, v112
	v_max_f32_e32 v108, 0, v108
	v_mul_f32_e32 v113, v109, v109
	v_max_f32_e32 v109, v114, v114
	v_mul_f32_e32 v114, v110, v110
	v_max_f32_e32 v110, v115, v115
	v_max_f32_e32 v111, v111, v111
	v_lshl_add_u64 v[116:117], s[2:3], 0, v[116:117]
	v_max_f32_e32 v112, 0, v112
	v_mul_f32_e32 v108, v108, v108
	v_max_f32_e32 v109, 0, v109
	v_max_f32_e32 v110, 0, v110
	v_max_f32_e32 v111, 0, v111
	v_max_f32_e32 v100, v100, v100
	v_lshl_add_u64 v[116:117], v[116:117], 0, v[152:153]
	v_mul_f32_e32 v112, v112, v112
	v_mul_f32_e32 v109, v109, v109
	v_mul_f32_e32 v110, v110, v110
	v_mul_f32_e32 v111, v111, v111
	v_cvt_pk_bf16_f32 v108, v112, v108
	v_max_f32_e32 v100, 0, v100
	v_max_f32_e32 v101, v101, v101
	v_max_f32_e32 v102, v102, v102
	v_cvt_pk_bf16_f32 v109, v109, v110
	v_cvt_pk_bf16_f32 v110, v118, v113
	v_cvt_pk_bf16_f32 v111, v114, v111
	global_store_dwordx4 v[116:117], v[108:111], off sc0 sc1
	v_max_f32_e32 v101, 0, v101
	v_max_f32_e32 v102, 0, v102
	v_mul_f32_e32 v108, v100, v100
	v_max_f32_e32 v100, v105, v105
	v_max_f32_e32 v104, v104, v104
	v_max_f32_e32 v100, 0, v100
	v_mul_f32_e32 v105, v101, v101
	v_max_f32_e32 v101, v106, v106
	v_mul_f32_e32 v106, v102, v102
	v_max_f32_e32 v102, v107, v107
	v_max_f32_e32 v103, v103, v103
	v_max_f32_e32 v104, 0, v104
	v_mul_f32_e32 v100, v100, v100
	v_max_f32_e32 v101, 0, v101
	v_max_f32_e32 v102, 0, v102
	v_max_f32_e32 v103, 0, v103
	v_mul_f32_e32 v104, v104, v104
	v_mul_f32_e32 v101, v101, v101
	v_mul_f32_e32 v102, v102, v102
	v_mul_f32_e32 v103, v103, v103
	v_cvt_pk_bf16_f32 v100, v104, v100
	v_max_f32_e32 v92, v92, v92
	v_cvt_pk_bf16_f32 v101, v101, v102
	v_cvt_pk_bf16_f32 v102, v108, v105
	v_cvt_pk_bf16_f32 v103, v106, v103
	global_store_dwordx4 v[116:117], v[100:103], off offset:256 sc0 sc1
	v_max_f32_e32 v92, 0, v92
	v_max_f32_e32 v93, v93, v93
	v_or_b32_e32 v100, 32, v148
	v_max_f32_e32 v94, v94, v94
	v_ashrrev_i32_e32 v101, 31, v100
	v_mul_f32_e32 v102, v92, v92
	v_max_f32_e32 v92, v97, v97
	v_max_f32_e32 v93, 0, v93
	v_max_f32_e32 v94, 0, v94
	v_lshlrev_b64 v[100:101], 14, v[100:101]
	v_max_f32_e32 v96, v96, v96
	v_max_f32_e32 v92, 0, v92
	v_mul_f32_e32 v97, v93, v93
	v_max_f32_e32 v93, v98, v98
	v_mul_f32_e32 v98, v94, v94
	v_max_f32_e32 v94, v99, v99
	v_max_f32_e32 v95, v95, v95
	v_lshl_add_u64 v[100:101], s[2:3], 0, v[100:101]
	v_max_f32_e32 v96, 0, v96
	v_mul_f32_e32 v92, v92, v92
	v_max_f32_e32 v93, 0, v93
	v_max_f32_e32 v94, 0, v94
	v_max_f32_e32 v95, 0, v95
	v_max_f32_e32 v84, v84, v84
	v_lshl_add_u64 v[100:101], v[100:101], 0, v[152:153]
	v_mul_f32_e32 v96, v96, v96
	v_mul_f32_e32 v93, v93, v93
	v_mul_f32_e32 v94, v94, v94
	v_mul_f32_e32 v95, v95, v95
	v_cvt_pk_bf16_f32 v92, v96, v92
	v_max_f32_e32 v84, 0, v84
	v_max_f32_e32 v85, v85, v85
	v_max_f32_e32 v86, v86, v86
	v_cvt_pk_bf16_f32 v93, v93, v94
	v_cvt_pk_bf16_f32 v94, v102, v97
	v_cvt_pk_bf16_f32 v95, v98, v95
	global_store_dwordx4 v[100:101], v[92:95], off sc0 sc1
	v_max_f32_e32 v85, 0, v85
	v_max_f32_e32 v86, 0, v86
	v_mul_f32_e32 v92, v84, v84
	v_max_f32_e32 v84, v89, v89
	v_max_f32_e32 v88, v88, v88
	v_max_f32_e32 v84, 0, v84
	v_mul_f32_e32 v89, v85, v85
	v_max_f32_e32 v85, v90, v90
	v_mul_f32_e32 v90, v86, v86
	v_max_f32_e32 v86, v91, v91
	v_max_f32_e32 v87, v87, v87
	v_max_f32_e32 v88, 0, v88
	v_mul_f32_e32 v84, v84, v84
	v_max_f32_e32 v85, 0, v85
	v_max_f32_e32 v86, 0, v86
	v_max_f32_e32 v87, 0, v87
	v_mul_f32_e32 v88, v88, v88
	v_mul_f32_e32 v85, v85, v85
	v_mul_f32_e32 v86, v86, v86
	v_mul_f32_e32 v87, v87, v87
	v_cvt_pk_bf16_f32 v84, v88, v84
	v_max_f32_e32 v76, v76, v76
	v_cvt_pk_bf16_f32 v85, v85, v86
	v_cvt_pk_bf16_f32 v86, v92, v89
	v_cvt_pk_bf16_f32 v87, v90, v87
	global_store_dwordx4 v[100:101], v[84:87], off offset:256 sc0 sc1
	v_max_f32_e32 v76, 0, v76
	v_max_f32_e32 v77, v77, v77
	v_or_b32_e32 v84, 48, v148
	v_max_f32_e32 v78, v78, v78
	v_ashrrev_i32_e32 v85, 31, v84
	v_mul_f32_e32 v86, v76, v76
	v_max_f32_e32 v76, v81, v81
	v_max_f32_e32 v77, 0, v77
	v_max_f32_e32 v78, 0, v78
	v_lshlrev_b64 v[84:85], 14, v[84:85]
	v_max_f32_e32 v80, v80, v80
	v_max_f32_e32 v76, 0, v76
	v_mul_f32_e32 v81, v77, v77
	v_max_f32_e32 v77, v82, v82
	v_mul_f32_e32 v82, v78, v78
	v_max_f32_e32 v78, v83, v83
	v_max_f32_e32 v79, v79, v79
	v_lshl_add_u64 v[84:85], s[2:3], 0, v[84:85]
	v_max_f32_e32 v80, 0, v80
	v_mul_f32_e32 v76, v76, v76
	v_max_f32_e32 v77, 0, v77
	v_max_f32_e32 v78, 0, v78
	v_max_f32_e32 v79, 0, v79
	v_max_f32_e32 v68, v68, v68
	v_max_f32_e32 v69, v69, v69
	v_max_f32_e32 v70, v70, v70
	v_lshl_add_u64 v[84:85], v[84:85], 0, v[152:153]
	v_mul_f32_e32 v80, v80, v80
	v_mul_f32_e32 v77, v77, v77
	v_mul_f32_e32 v78, v78, v78
	v_mul_f32_e32 v79, v79, v79
	v_cvt_pk_bf16_f32 v76, v80, v76
	v_max_f32_e32 v68, 0, v68
	v_max_f32_e32 v69, 0, v69
	v_max_f32_e32 v70, 0, v70
	v_cvt_pk_bf16_f32 v77, v77, v78
	v_cvt_pk_bf16_f32 v78, v86, v81
	v_cvt_pk_bf16_f32 v79, v82, v79
	global_store_dwordx4 v[84:85], v[76:79], off sc0 sc1
	v_max_f32_e32 v72, v72, v72
	v_max_f32_e32 v71, v71, v71
	v_mul_f32_e32 v76, v68, v68
	v_max_f32_e32 v68, v73, v73
	v_mul_f32_e32 v73, v69, v69
	v_max_f32_e32 v69, v74, v74
	v_mul_f32_e32 v74, v70, v70
	v_max_f32_e32 v70, v75, v75
	v_max_f32_e32 v68, 0, v68
	v_max_f32_e32 v69, 0, v69
	v_max_f32_e32 v70, 0, v70
	v_max_f32_e32 v72, 0, v72
	v_mul_f32_e32 v68, v68, v68
	v_mul_f32_e32 v69, v69, v69
	v_max_f32_e32 v71, 0, v71
	v_mul_f32_e32 v70, v70, v70
	v_max_f32_e32 v60, v60, v60
	v_mul_f32_e32 v72, v72, v72
	v_mul_f32_e32 v71, v71, v71
	v_cvt_pk_bf16_f32 v68, v72, v68
	v_cvt_pk_bf16_f32 v69, v69, v70
	v_cvt_pk_bf16_f32 v70, v76, v73
	v_max_f32_e32 v60, 0, v60
	v_max_f32_e32 v61, v61, v61
	v_max_f32_e32 v62, v62, v62
	v_cvt_pk_bf16_f32 v71, v74, v71
	global_store_dwordx4 v[84:85], v[68:71], off offset:256 sc0 sc1
	v_max_f32_e32 v64, v64, v64
	v_max_f32_e32 v61, 0, v61
	v_mul_f32_e32 v70, v60, v60
	v_max_f32_e32 v60, v65, v65
	v_max_f32_e32 v62, 0, v62
	v_max_f32_e32 v64, 0, v64
	v_max_f32_e32 v60, 0, v60
	v_mul_f32_e32 v65, v61, v61
	v_max_f32_e32 v61, v66, v66
	v_mul_f32_e32 v66, v62, v62
	v_max_f32_e32 v62, v67, v67
	v_mul_f32_e32 v64, v64, v64
	v_mul_f32_e32 v60, v60, v60
	v_max_f32_e32 v61, 0, v61
	v_max_f32_e32 v62, 0, v62
	v_max_f32_e32 v63, v63, v63
	s_mov_b32 s11, 0x200000
	v_mul_f32_e32 v61, v61, v61
	v_max_f32_e32 v63, 0, v63
	v_mul_f32_e32 v62, v62, v62
	v_cvt_pk_bf16_f32 v60, v64, v60
	v_add_co_u32_e32 v64, vcc, s11, v142
	v_max_f32_e32 v52, v52, v52
	v_max_f32_e32 v53, v53, v53
	v_max_f32_e32 v54, v54, v54
	v_mul_f32_e32 v63, v63, v63
	v_cvt_pk_bf16_f32 v61, v61, v62
	v_cvt_pk_bf16_f32 v62, v70, v65
	v_addc_co_u32_e32 v65, vcc, 0, v143, vcc
	v_max_f32_e32 v52, 0, v52
	v_max_f32_e32 v53, 0, v53
	v_max_f32_e32 v54, 0, v54
	v_cvt_pk_bf16_f32 v63, v66, v63
	global_store_dwordx4 v[64:65], v[60:63], off sc0 sc1
	v_max_f32_e32 v56, v56, v56
	v_max_f32_e32 v55, v55, v55
	v_mul_f32_e32 v60, v52, v52
	v_max_f32_e32 v52, v57, v57
	v_mul_f32_e32 v57, v53, v53
	v_max_f32_e32 v53, v58, v58
	v_mul_f32_e32 v58, v54, v54
	v_max_f32_e32 v54, v59, v59
	v_max_f32_e32 v52, 0, v52
	v_max_f32_e32 v53, 0, v53
	v_max_f32_e32 v54, 0, v54
	s_mov_b64 s[18:19], 0x200000
	v_max_f32_e32 v56, 0, v56
	v_mul_f32_e32 v52, v52, v52
	v_mul_f32_e32 v53, v53, v53
	v_max_f32_e32 v55, 0, v55
	v_mul_f32_e32 v54, v54, v54
	v_max_f32_e32 v44, v44, v44
	v_lshl_add_u64 v[68:69], v[142:143], 0, s[18:19]
	v_mul_f32_e32 v56, v56, v56
	v_mul_f32_e32 v55, v55, v55
	v_cvt_pk_bf16_f32 v52, v56, v52
	v_cvt_pk_bf16_f32 v53, v53, v54
	v_cvt_pk_bf16_f32 v54, v60, v57
	v_max_f32_e32 v44, 0, v44
	v_max_f32_e32 v45, v45, v45
	v_max_f32_e32 v46, v46, v46
	v_cvt_pk_bf16_f32 v55, v58, v55
	global_store_dwordx4 v[68:69], v[52:55], off offset:256 sc0 sc1
	v_max_f32_e32 v48, v48, v48
	v_max_f32_e32 v45, 0, v45
	v_mul_f32_e32 v54, v44, v44
	v_max_f32_e32 v44, v49, v49
	v_max_f32_e32 v46, 0, v46
	v_max_f32_e32 v48, 0, v48
	v_max_f32_e32 v44, 0, v44
	v_mul_f32_e32 v49, v45, v45
	v_max_f32_e32 v45, v50, v50
	v_mul_f32_e32 v50, v46, v46
	v_max_f32_e32 v46, v51, v51
	v_mul_f32_e32 v48, v48, v48
	v_mul_f32_e32 v44, v44, v44
	v_max_f32_e32 v45, 0, v45
	v_max_f32_e32 v46, 0, v46
	v_max_f32_e32 v47, v47, v47
	s_mov_b32 s11, 0x240000
	v_mul_f32_e32 v45, v45, v45
	v_max_f32_e32 v47, 0, v47
	v_mul_f32_e32 v46, v46, v46
	v_cvt_pk_bf16_f32 v44, v48, v44
	v_add_co_u32_e32 v48, vcc, s11, v142
	v_max_f32_e32 v36, v36, v36
	v_max_f32_e32 v37, v37, v37
	v_max_f32_e32 v38, v38, v38
	v_mul_f32_e32 v47, v47, v47
	v_cvt_pk_bf16_f32 v45, v45, v46
	v_cvt_pk_bf16_f32 v46, v54, v49
	v_addc_co_u32_e32 v49, vcc, 0, v143, vcc
	v_max_f32_e32 v36, 0, v36
	v_max_f32_e32 v37, 0, v37
	v_max_f32_e32 v38, 0, v38
	v_cvt_pk_bf16_f32 v47, v50, v47
	global_store_dwordx4 v[48:49], v[44:47], off sc0 sc1
	v_max_f32_e32 v40, v40, v40
	v_max_f32_e32 v39, v39, v39
	v_mul_f32_e32 v44, v36, v36
	v_max_f32_e32 v36, v41, v41
	v_mul_f32_e32 v41, v37, v37
	v_max_f32_e32 v37, v42, v42
	v_mul_f32_e32 v42, v38, v38
	v_max_f32_e32 v38, v43, v43
	v_max_f32_e32 v36, 0, v36
	v_max_f32_e32 v37, 0, v37
	v_max_f32_e32 v38, 0, v38
	s_mov_b64 s[18:19], 0x240000
	v_max_f32_e32 v40, 0, v40
	v_mul_f32_e32 v36, v36, v36
	v_mul_f32_e32 v37, v37, v37
	v_max_f32_e32 v39, 0, v39
	v_mul_f32_e32 v38, v38, v38
	v_max_f32_e32 v28, v28, v28
	v_lshl_add_u64 v[52:53], v[142:143], 0, s[18:19]
	v_mul_f32_e32 v40, v40, v40
	v_mul_f32_e32 v39, v39, v39
	v_cvt_pk_bf16_f32 v36, v40, v36
	v_cvt_pk_bf16_f32 v37, v37, v38
	v_cvt_pk_bf16_f32 v38, v44, v41
	v_max_f32_e32 v28, 0, v28
	v_max_f32_e32 v29, v29, v29
	v_max_f32_e32 v30, v30, v30
	v_cvt_pk_bf16_f32 v39, v42, v39
	global_store_dwordx4 v[52:53], v[36:39], off offset:256 sc0 sc1
	v_max_f32_e32 v32, v32, v32
	v_max_f32_e32 v29, 0, v29
	v_mul_f32_e32 v38, v28, v28
	v_max_f32_e32 v28, v33, v33
	v_max_f32_e32 v30, 0, v30
	v_max_f32_e32 v32, 0, v32
	v_max_f32_e32 v28, 0, v28
	v_mul_f32_e32 v33, v29, v29
	v_max_f32_e32 v29, v34, v34
	v_mul_f32_e32 v34, v30, v30
	v_max_f32_e32 v30, v35, v35
	v_mul_f32_e32 v32, v32, v32
	v_mul_f32_e32 v28, v28, v28
	v_max_f32_e32 v29, 0, v29
	v_max_f32_e32 v30, 0, v30
	v_max_f32_e32 v31, v31, v31
	s_mov_b32 s11, 0x280000
	v_mul_f32_e32 v29, v29, v29
	v_max_f32_e32 v31, 0, v31
	v_mul_f32_e32 v30, v30, v30
	v_cvt_pk_bf16_f32 v28, v32, v28
	v_add_co_u32_e32 v32, vcc, s11, v142
	v_max_f32_e32 v20, v20, v20
	v_max_f32_e32 v21, v21, v21
	v_max_f32_e32 v22, v22, v22
	v_mul_f32_e32 v31, v31, v31
	v_cvt_pk_bf16_f32 v29, v29, v30
	v_cvt_pk_bf16_f32 v30, v38, v33
	v_addc_co_u32_e32 v33, vcc, 0, v143, vcc
	v_max_f32_e32 v20, 0, v20
	v_max_f32_e32 v21, 0, v21
	v_max_f32_e32 v22, 0, v22
	v_cvt_pk_bf16_f32 v31, v34, v31
	global_store_dwordx4 v[32:33], v[28:31], off sc0 sc1
	v_max_f32_e32 v24, v24, v24
	v_max_f32_e32 v23, v23, v23
	v_mul_f32_e32 v28, v20, v20
	v_max_f32_e32 v20, v25, v25
	v_mul_f32_e32 v25, v21, v21
	v_max_f32_e32 v21, v26, v26
	v_mul_f32_e32 v26, v22, v22
	v_max_f32_e32 v22, v27, v27
	v_max_f32_e32 v20, 0, v20
	v_max_f32_e32 v21, 0, v21
	v_max_f32_e32 v22, 0, v22
	s_mov_b64 s[18:19], 0x280000
	v_max_f32_e32 v24, 0, v24
	v_mul_f32_e32 v20, v20, v20
	v_mul_f32_e32 v21, v21, v21
	v_max_f32_e32 v23, 0, v23
	v_mul_f32_e32 v22, v22, v22
	v_max_f32_e32 v12, v12, v12
	v_lshl_add_u64 v[36:37], v[142:143], 0, s[18:19]
	v_mul_f32_e32 v24, v24, v24
	v_mul_f32_e32 v23, v23, v23
	v_cvt_pk_bf16_f32 v20, v24, v20
	v_cvt_pk_bf16_f32 v21, v21, v22
	v_cvt_pk_bf16_f32 v22, v28, v25
	v_max_f32_e32 v12, 0, v12
	v_max_f32_e32 v13, v13, v13
	v_max_f32_e32 v14, v14, v14
	v_cvt_pk_bf16_f32 v23, v26, v23
	global_store_dwordx4 v[36:37], v[20:23], off offset:256 sc0 sc1
	v_max_f32_e32 v16, v16, v16
	v_max_f32_e32 v13, 0, v13
	v_mul_f32_e32 v22, v12, v12
	v_max_f32_e32 v12, v17, v17
	v_max_f32_e32 v14, 0, v14
	v_max_f32_e32 v16, 0, v16
	v_max_f32_e32 v12, 0, v12
	v_mul_f32_e32 v17, v13, v13
	v_max_f32_e32 v13, v18, v18
	v_mul_f32_e32 v18, v14, v14
	v_max_f32_e32 v14, v19, v19
	v_mul_f32_e32 v16, v16, v16
	v_mul_f32_e32 v12, v12, v12
	v_max_f32_e32 v13, 0, v13
	v_max_f32_e32 v14, 0, v14
	v_max_f32_e32 v15, v15, v15
	s_mov_b32 s11, 0x2c0000
	v_mul_f32_e32 v13, v13, v13
	v_max_f32_e32 v15, 0, v15
	v_mul_f32_e32 v14, v14, v14
	v_cvt_pk_bf16_f32 v12, v16, v12
	v_add_co_u32_e32 v16, vcc, s11, v142
	v_max_f32_e32 v4, v4, v4
	v_max_f32_e32 v5, v5, v5
	v_max_f32_e32 v6, v6, v6
	v_mul_f32_e32 v15, v15, v15
	v_cvt_pk_bf16_f32 v13, v13, v14
	v_cvt_pk_bf16_f32 v14, v22, v17
	v_addc_co_u32_e32 v17, vcc, 0, v143, vcc
	v_max_f32_e32 v4, 0, v4
	v_max_f32_e32 v5, 0, v5
	v_max_f32_e32 v6, 0, v6
	v_cvt_pk_bf16_f32 v15, v18, v15
	global_store_dwordx4 v[16:17], v[12:15], off sc0 sc1
	v_max_f32_e32 v7, v7, v7
	s_mov_b64 s[18:19], 0x2c0000
	v_mul_f32_e32 v12, v4, v4
	v_max_f32_e32 v4, v9, v9
	v_mul_f32_e32 v9, v5, v5
	v_max_f32_e32 v5, v10, v10
	v_mul_f32_e32 v10, v6, v6
	v_max_f32_e32 v6, v11, v11
	v_max_f32_e32 v8, v8, v8
	v_max_f32_e32 v4, 0, v4
	v_max_f32_e32 v5, 0, v5
	v_max_f32_e32 v6, 0, v6
	v_max_f32_e32 v7, 0, v7
	v_readlane_b32 s54, v250, 52
	v_lshl_add_u64 v[20:21], v[142:143], 0, s[18:19]
	v_max_f32_e32 v8, 0, v8
	v_mul_f32_e32 v4, v4, v4
	v_mul_f32_e32 v5, v5, v5
	v_mul_f32_e32 v6, v6, v6
	v_mul_f32_e32 v7, v7, v7
	s_andn2_b64 vcc, exec, s[40:41]
	s_mov_b64 s[18:19], -1
	s_mov_b64 s[56:57], 0x40000
	v_readlane_b32 s55, v250, 53
	v_mul_f32_e32 v8, v8, v8
	v_cvt_pk_bf16_f32 v4, v8, v4
	v_cvt_pk_bf16_f32 v5, v5, v6
	v_cvt_pk_bf16_f32 v6, v12, v9
	v_cvt_pk_bf16_f32 v7, v10, v7
	global_store_dwordx4 v[20:21], v[4:7], off offset:256 sc0 sc1
	s_branch .Ljoin_ff1

.LBB0_1295:
	s_add_i32 s54, s24, 2
	s_add_u32 s25, s20, 0xffe00080
	s_addc_u32 s26, s21, -1
	s_add_i32 s55, 0, 0x10000
	s_cmp_eq_u32 s11, s24
	s_cselect_b32 s27, s13, s26
	s_cselect_b32 s26, s12, s25
	v_add_u32_e32 v2, s55, v1
	s_cselect_b32 s25, s19, s53
	s_cselect_b32 s24, s18, s17
	s_add_i32 s58, 0, 0x14000
	ds_read_b128 v[146:149], v2
	ds_read_b128 v[150:153], v2 offset:1024
	ds_read_b128 v[154:157], v2 offset:2048
	ds_read_b128 v[158:161], v2 offset:3072
	v_add_u32_e32 v2, s58, v1
	ds_read_b128 v[162:165], v2
	ds_read_b128 v[180:183], v2 offset:1024
	ds_read_b128 v[184:187], v2 offset:2048
	ds_read_b128 v[188:191], v2 offset:3072
	v_lshl_add_u64 v[166:167], s[20:21], 0, v[140:141]
	s_add_i32 m0, s40, 0xc000
	ds_read_b128 v[192:195], v145
	ds_read_b128 v[196:199], v145 offset:1024
	ds_read_b128 v[208:211], v145 offset:2048
	ds_read_b128 v[212:215], v145 offset:3072
	ds_read_b128 v[216:219], v145 offset:4096
	ds_read_b128 v[220:223], v145 offset:5120
	ds_read_b128 v[224:227], v145 offset:6144
	ds_read_b128 v[228:231], v145 offset:7168
	global_load_lds_dwordx4 v[166:167], off
	v_lshl_add_u64 v[166:167], s[20:21], 0, v[142:143]
	s_add_i32 m0, s40, 0xe000
	s_nop 0
	global_load_lds_dwordx4 v[166:167], off
	s_waitcnt vmcnt(8)
	s_waitcnt lgkmcnt(0)
	s_barrier
	s_waitcnt lgkmcnt(0)
	v_mfma_f32_16x16x32_bf16 v[128:131], v[146:149], v[192:195], v[128:131]
	v_mfma_f32_16x16x32_bf16 v[124:127], v[154:157], v[192:195], v[124:127]
	v_mfma_f32_16x16x32_bf16 v[120:123], v[146:149], v[208:211], v[120:123]
	v_mfma_f32_16x16x32_bf16 v[112:115], v[154:157], v[208:211], v[112:115]
	v_mfma_f32_16x16x32_bf16 v[104:107], v[146:149], v[216:219], v[104:107]
	v_mfma_f32_16x16x32_bf16 v[96:99], v[154:157], v[216:219], v[96:99]
	v_mfma_f32_16x16x32_bf16 v[88:91], v[146:149], v[224:227], v[88:91]
	v_mfma_f32_16x16x32_bf16 v[80:83], v[154:157], v[224:227], v[80:83]
	v_mfma_f32_16x16x32_bf16 v[128:131], v[150:153], v[196:199], v[128:131]
	v_mfma_f32_16x16x32_bf16 v[124:127], v[158:161], v[196:199], v[124:127]
	v_mfma_f32_16x16x32_bf16 v[120:123], v[150:153], v[212:215], v[120:123]
	v_mfma_f32_16x16x32_bf16 v[112:115], v[158:161], v[212:215], v[112:115]
	v_mfma_f32_16x16x32_bf16 v[104:107], v[150:153], v[220:223], v[104:107]
	v_mfma_f32_16x16x32_bf16 v[96:99], v[158:161], v[220:223], v[96:99]
	v_mfma_f32_16x16x32_bf16 v[88:91], v[150:153], v[228:231], v[88:91]
	v_mfma_f32_16x16x32_bf16 v[80:83], v[158:161], v[228:231], v[80:83]
	v_mfma_f32_16x16x32_bf16 v[116:119], v[162:165], v[192:195], v[116:119]
	v_mfma_f32_16x16x32_bf16 v[108:111], v[184:187], v[192:195], v[108:111]
	v_mfma_f32_16x16x32_bf16 v[100:103], v[162:165], v[208:211], v[100:103]
	v_mfma_f32_16x16x32_bf16 v[92:95], v[184:187], v[208:211], v[92:95]
	v_mfma_f32_16x16x32_bf16 v[84:87], v[162:165], v[216:219], v[84:87]
	v_mfma_f32_16x16x32_bf16 v[76:79], v[184:187], v[216:219], v[76:79]
	v_mfma_f32_16x16x32_bf16 v[72:75], v[162:165], v[224:227], v[72:75]
	v_mfma_f32_16x16x32_bf16 v[68:71], v[184:187], v[224:227], v[68:71]
	v_mfma_f32_16x16x32_bf16 v[116:119], v[180:183], v[196:199], v[116:119]
	v_mfma_f32_16x16x32_bf16 v[108:111], v[188:191], v[196:199], v[108:111]
	v_mfma_f32_16x16x32_bf16 v[100:103], v[180:183], v[212:215], v[100:103]
	v_mfma_f32_16x16x32_bf16 v[92:95], v[188:191], v[212:215], v[92:95]
	v_mfma_f32_16x16x32_bf16 v[84:87], v[180:183], v[220:223], v[84:87]
	v_mfma_f32_16x16x32_bf16 v[76:79], v[188:191], v[220:223], v[76:79]
	v_mfma_f32_16x16x32_bf16 v[72:75], v[180:183], v[228:231], v[72:75]
	v_mfma_f32_16x16x32_bf16 v[68:71], v[188:191], v[228:231], v[68:71]
	s_barrier
	s_add_i32 s55, s55, s35
	v_lshl_add_u64 v[166:167], s[24:25], 0, v[136:137]
	s_mov_b32 m0, s55
	ds_read_b128 v[192:195], v145 offset:16384
	ds_read_b128 v[196:199], v145 offset:17408
	ds_read_b128 v[208:211], v145 offset:18432
	ds_read_b128 v[212:215], v145 offset:19456
	ds_read_b128 v[216:219], v145 offset:20480
	ds_read_b128 v[220:223], v145 offset:21504
	ds_read_b128 v[224:227], v145 offset:22528
	ds_read_b128 v[228:231], v145 offset:23552
	global_load_lds_dwordx4 v[166:167], off
	s_add_i32 m0, s55, 0x2000
	s_add_u32 s56, s24, 0x200000
	v_lshl_add_u64 v[232:233], s[24:25], 0, v[132:133]
	s_addc_u32 s57, s25, 0
	s_add_i32 s55, s58, s35
	global_load_lds_dwordx4 v[232:233], off
	v_lshl_add_u64 v[234:235], s[56:57], 0, v[136:137]
	s_mov_b32 m0, s55
	v_lshl_add_u64 v[236:237], s[26:27], 0, v[134:135]
	global_load_lds_dwordx4 v[234:235], off
	v_lshl_add_u64 v[234:235], s[56:57], 0, v[132:133]
	s_add_i32 m0, s55, 0x2000
	s_nop 0
	global_load_lds_dwordx4 v[234:235], off
	v_lshl_add_u64 v[234:235], s[26:27], 0, v[138:139]
	s_mov_b32 m0, s40
	s_nop 0
	global_load_lds_dwordx4 v[234:235], off
	s_mov_b32 m0, s41
	s_nop 0
	global_load_lds_dwordx4 v[236:237], off
	s_waitcnt vmcnt(8)
	s_waitcnt lgkmcnt(0)
	s_barrier
	s_waitcnt lgkmcnt(0)
	v_mfma_f32_16x16x32_bf16 v[64:67], v[146:149], v[192:195], v[64:67]
	v_mfma_f32_16x16x32_bf16 v[60:63], v[154:157], v[192:195], v[60:63]
	v_mfma_f32_16x16x32_bf16 v[56:59], v[146:149], v[208:211], v[56:59]
	v_mfma_f32_16x16x32_bf16 v[48:51], v[154:157], v[208:211], v[48:51]
	v_mfma_f32_16x16x32_bf16 v[40:43], v[146:149], v[216:219], v[40:43]
	v_mfma_f32_16x16x32_bf16 v[32:35], v[154:157], v[216:219], v[32:35]
	v_mfma_f32_16x16x32_bf16 v[24:27], v[146:149], v[224:227], v[24:27]
	v_mfma_f32_16x16x32_bf16 v[16:19], v[154:157], v[224:227], v[16:19]
	v_mfma_f32_16x16x32_bf16 v[64:67], v[150:153], v[196:199], v[64:67]
	v_mfma_f32_16x16x32_bf16 v[60:63], v[158:161], v[196:199], v[60:63]
	v_mfma_f32_16x16x32_bf16 v[56:59], v[150:153], v[212:215], v[56:59]
	v_mfma_f32_16x16x32_bf16 v[48:51], v[158:161], v[212:215], v[48:51]
	v_mfma_f32_16x16x32_bf16 v[40:43], v[150:153], v[220:223], v[40:43]
	v_mfma_f32_16x16x32_bf16 v[32:35], v[158:161], v[220:223], v[32:35]
	v_mfma_f32_16x16x32_bf16 v[24:27], v[150:153], v[228:231], v[24:27]
	v_mfma_f32_16x16x32_bf16 v[16:19], v[158:161], v[228:231], v[16:19]
	v_mfma_f32_16x16x32_bf16 v[52:55], v[162:165], v[192:195], v[52:55]
	v_mfma_f32_16x16x32_bf16 v[44:47], v[184:187], v[192:195], v[44:47]
	v_mfma_f32_16x16x32_bf16 v[36:39], v[162:165], v[208:211], v[36:39]
	v_mfma_f32_16x16x32_bf16 v[28:31], v[184:187], v[208:211], v[28:31]
	v_mfma_f32_16x16x32_bf16 v[20:23], v[162:165], v[216:219], v[20:23]
	v_mfma_f32_16x16x32_bf16 v[12:15], v[184:187], v[216:219], v[12:15]
	v_mfma_f32_16x16x32_bf16 v[8:11], v[162:165], v[224:227], v[8:11]
	v_mfma_f32_16x16x32_bf16 v[4:7], v[184:187], v[224:227], v[4:7]
	v_mfma_f32_16x16x32_bf16 v[52:55], v[180:183], v[196:199], v[52:55]
	v_mfma_f32_16x16x32_bf16 v[44:47], v[188:191], v[196:199], v[44:47]
	v_mfma_f32_16x16x32_bf16 v[36:39], v[180:183], v[212:215], v[36:39]
	v_mfma_f32_16x16x32_bf16 v[28:31], v[188:191], v[212:215], v[28:31]
	v_mfma_f32_16x16x32_bf16 v[20:23], v[180:183], v[220:223], v[20:23]
	v_mfma_f32_16x16x32_bf16 v[12:15], v[188:191], v[220:223], v[12:15]
	v_mfma_f32_16x16x32_bf16 v[8:11], v[180:183], v[228:231], v[8:11]
	v_mfma_f32_16x16x32_bf16 v[4:7], v[188:191], v[228:231], v[4:7]
	s_barrier
	s_add_i32 s55, 0, 0x18000
	v_add_u32_e32 v2, s55, v1
	s_add_i32 s56, 0, 0x1c000
	ds_read_b128 v[146:149], v2
	ds_read_b128 v[150:153], v2 offset:1024
	ds_read_b128 v[154:157], v2 offset:2048
	ds_read_b128 v[158:161], v2 offset:3072
	v_add_u32_e32 v2, s56, v1
	ds_read_b128 v[162:165], v2
	ds_read_b128 v[180:183], v2 offset:1024
	ds_read_b128 v[184:187], v2 offset:2048
	ds_read_b128 v[188:191], v2 offset:3072
	s_add_u32 s26, s26, 0x200000
	s_addc_u32 s27, s27, 0
	s_mov_b32 m0, s42
	v_lshl_add_u64 v[238:239], s[26:27], 0, v[138:139]
	ds_read_b128 v[192:195], v145 offset:32768
	ds_read_b128 v[196:199], v145 offset:33792
	ds_read_b128 v[208:211], v145 offset:34816
	ds_read_b128 v[212:215], v145 offset:35840
	ds_read_b128 v[216:219], v145 offset:36864
	ds_read_b128 v[220:223], v145 offset:37888
	ds_read_b128 v[224:227], v145 offset:38912
	ds_read_b128 v[228:231], v145 offset:39936
	global_load_lds_dwordx4 v[238:239], off
	v_lshl_add_u64 v[238:239], s[26:27], 0, v[134:135]
	s_mov_b32 m0, s43
	s_nop 0
	global_load_lds_dwordx4 v[238:239], off
	s_waitcnt vmcnt(8)
	s_waitcnt lgkmcnt(0)
	s_barrier
	s_waitcnt lgkmcnt(0)
	v_mfma_f32_16x16x32_bf16 v[128:131], v[146:149], v[192:195], v[128:131]
	v_mfma_f32_16x16x32_bf16 v[124:127], v[154:157], v[192:195], v[124:127]
	v_mfma_f32_16x16x32_bf16 v[120:123], v[146:149], v[208:211], v[120:123]
	v_mfma_f32_16x16x32_bf16 v[112:115], v[154:157], v[208:211], v[112:115]
	v_mfma_f32_16x16x32_bf16 v[104:107], v[146:149], v[216:219], v[104:107]
	v_mfma_f32_16x16x32_bf16 v[96:99], v[154:157], v[216:219], v[96:99]
	v_mfma_f32_16x16x32_bf16 v[88:91], v[146:149], v[224:227], v[88:91]
	v_mfma_f32_16x16x32_bf16 v[80:83], v[154:157], v[224:227], v[80:83]
	v_mfma_f32_16x16x32_bf16 v[128:131], v[150:153], v[196:199], v[128:131]
	v_mfma_f32_16x16x32_bf16 v[124:127], v[158:161], v[196:199], v[124:127]
	v_mfma_f32_16x16x32_bf16 v[120:123], v[150:153], v[212:215], v[120:123]
	v_mfma_f32_16x16x32_bf16 v[112:115], v[158:161], v[212:215], v[112:115]
	v_mfma_f32_16x16x32_bf16 v[104:107], v[150:153], v[220:223], v[104:107]
	v_mfma_f32_16x16x32_bf16 v[96:99], v[158:161], v[220:223], v[96:99]
	v_mfma_f32_16x16x32_bf16 v[88:91], v[150:153], v[228:231], v[88:91]
	v_mfma_f32_16x16x32_bf16 v[80:83], v[158:161], v[228:231], v[80:83]
	v_mfma_f32_16x16x32_bf16 v[116:119], v[162:165], v[192:195], v[116:119]
	v_mfma_f32_16x16x32_bf16 v[108:111], v[184:187], v[192:195], v[108:111]
	v_mfma_f32_16x16x32_bf16 v[100:103], v[162:165], v[208:211], v[100:103]
	v_mfma_f32_16x16x32_bf16 v[92:95], v[184:187], v[208:211], v[92:95]
	v_mfma_f32_16x16x32_bf16 v[84:87], v[162:165], v[216:219], v[84:87]
	v_mfma_f32_16x16x32_bf16 v[76:79], v[184:187], v[216:219], v[76:79]
	v_mfma_f32_16x16x32_bf16 v[72:75], v[162:165], v[224:227], v[72:75]
	v_mfma_f32_16x16x32_bf16 v[68:71], v[184:187], v[224:227], v[68:71]
	v_mfma_f32_16x16x32_bf16 v[116:119], v[180:183], v[196:199], v[116:119]
	v_mfma_f32_16x16x32_bf16 v[108:111], v[188:191], v[196:199], v[108:111]
	v_mfma_f32_16x16x32_bf16 v[100:103], v[180:183], v[212:215], v[100:103]
	v_mfma_f32_16x16x32_bf16 v[92:95], v[188:191], v[212:215], v[92:95]
	v_mfma_f32_16x16x32_bf16 v[84:87], v[180:183], v[220:223], v[84:87]
	v_mfma_f32_16x16x32_bf16 v[76:79], v[188:191], v[220:223], v[76:79]
	v_mfma_f32_16x16x32_bf16 v[72:75], v[180:183], v[228:231], v[72:75]
	v_mfma_f32_16x16x32_bf16 v[68:71], v[188:191], v[228:231], v[68:71]
	s_barrier
	s_add_i32 s26, s55, s35
	v_lshl_add_u64 v[166:167], v[166:167], 0, s[2:3]
	s_mov_b32 m0, s26
	ds_read_b128 v[192:195], v145 offset:49152
	ds_read_b128 v[196:199], v145 offset:50176
	ds_read_b128 v[208:211], v145 offset:51200
	ds_read_b128 v[212:215], v145 offset:52224
	ds_read_b128 v[216:219], v145 offset:53248
	ds_read_b128 v[220:223], v145 offset:54272
	ds_read_b128 v[224:227], v145 offset:55296
	ds_read_b128 v[228:231], v145 offset:56320
	global_load_lds_dwordx4 v[166:167], off
	s_add_i32 m0, s26, 0x2000
	s_add_u32 s24, s24, 0x200080
	v_lshl_add_u64 v[166:167], v[232:233], 0, s[2:3]
	s_addc_u32 s25, s25, 0
	s_add_i32 s26, s56, s35
	global_load_lds_dwordx4 v[166:167], off
	v_lshl_add_u64 v[166:167], s[24:25], 0, v[136:137]
	s_mov_b32 m0, s26
	s_nop 0
	global_load_lds_dwordx4 v[166:167], off
	v_lshl_add_u64 v[166:167], s[24:25], 0, v[132:133]
	s_add_i32 m0, s26, 0x2000
	s_nop 0
	global_load_lds_dwordx4 v[166:167], off
	v_lshl_add_u64 v[166:167], v[234:235], 0, s[2:3]
	s_mov_b32 m0, s44
	s_nop 0
	global_load_lds_dwordx4 v[166:167], off
	v_lshl_add_u64 v[166:167], v[236:237], 0, s[2:3]
	s_mov_b32 m0, s45
	s_nop 0
	global_load_lds_dwordx4 v[166:167], off
	s_waitcnt vmcnt(8)
	s_waitcnt lgkmcnt(0)
	s_barrier
	s_waitcnt lgkmcnt(0)
	v_mfma_f32_16x16x32_bf16 v[64:67], v[146:149], v[192:195], v[64:67]
	v_mfma_f32_16x16x32_bf16 v[60:63], v[154:157], v[192:195], v[60:63]
	v_mfma_f32_16x16x32_bf16 v[56:59], v[146:149], v[208:211], v[56:59]
	v_mfma_f32_16x16x32_bf16 v[48:51], v[154:157], v[208:211], v[48:51]
	v_mfma_f32_16x16x32_bf16 v[40:43], v[146:149], v[216:219], v[40:43]
	v_mfma_f32_16x16x32_bf16 v[32:35], v[154:157], v[216:219], v[32:35]
	v_mfma_f32_16x16x32_bf16 v[24:27], v[146:149], v[224:227], v[24:27]
	v_mfma_f32_16x16x32_bf16 v[16:19], v[154:157], v[224:227], v[16:19]
	v_mfma_f32_16x16x32_bf16 v[64:67], v[150:153], v[196:199], v[64:67]
	v_mfma_f32_16x16x32_bf16 v[60:63], v[158:161], v[196:199], v[60:63]
	v_mfma_f32_16x16x32_bf16 v[56:59], v[150:153], v[212:215], v[56:59]
	v_mfma_f32_16x16x32_bf16 v[48:51], v[158:161], v[212:215], v[48:51]
	v_mfma_f32_16x16x32_bf16 v[40:43], v[150:153], v[220:223], v[40:43]
	v_mfma_f32_16x16x32_bf16 v[32:35], v[158:161], v[220:223], v[32:35]
	v_mfma_f32_16x16x32_bf16 v[24:27], v[150:153], v[228:231], v[24:27]
	v_mfma_f32_16x16x32_bf16 v[16:19], v[158:161], v[228:231], v[16:19]
	v_mfma_f32_16x16x32_bf16 v[52:55], v[162:165], v[192:195], v[52:55]
	v_mfma_f32_16x16x32_bf16 v[44:47], v[184:187], v[192:195], v[44:47]
	v_mfma_f32_16x16x32_bf16 v[36:39], v[162:165], v[208:211], v[36:39]
	v_mfma_f32_16x16x32_bf16 v[28:31], v[184:187], v[208:211], v[28:31]
	v_mfma_f32_16x16x32_bf16 v[20:23], v[162:165], v[216:219], v[20:23]
	v_mfma_f32_16x16x32_bf16 v[12:15], v[184:187], v[216:219], v[12:15]
	v_mfma_f32_16x16x32_bf16 v[8:11], v[162:165], v[224:227], v[8:11]
	v_mfma_f32_16x16x32_bf16 v[4:7], v[184:187], v[224:227], v[4:7]
	v_mfma_f32_16x16x32_bf16 v[52:55], v[180:183], v[196:199], v[52:55]
	v_mfma_f32_16x16x32_bf16 v[44:47], v[188:191], v[196:199], v[44:47]
	v_mfma_f32_16x16x32_bf16 v[36:39], v[180:183], v[212:215], v[36:39]
	v_mfma_f32_16x16x32_bf16 v[28:31], v[188:191], v[212:215], v[28:31]
	v_mfma_f32_16x16x32_bf16 v[20:23], v[180:183], v[220:223], v[20:23]
	v_mfma_f32_16x16x32_bf16 v[12:15], v[188:191], v[220:223], v[12:15]
	v_mfma_f32_16x16x32_bf16 v[8:11], v[180:183], v[228:231], v[8:11]
	v_mfma_f32_16x16x32_bf16 v[4:7], v[188:191], v[228:231], v[4:7]
	s_barrier
	s_add_u32 s20, s20, 0x100
	s_addc_u32 s21, s21, 0
	s_add_u32 s17, s17, 0x100
	s_addc_u32 s53, s53, 0
	s_cmp_ge_u32 s54, s51
	s_mov_b32 s24, s54
	s_cbranch_scc0 .LBB0_1295
	s_and_b64 vcc, exec, s[8:9]
	s_cbranch_vccz .LBB0_1298
	s_barrier
.LBB0_1298:
	s_cmp_eq_u32 s51, 32
	s_cbranch_scc1 .Llast_ff2
	v_cvt_f32_u32_e32 v2, s51
	v_cvt_f32_u32_e32 v148, s52
	v_cvt_pk_bf16_f32 v146, v128, v129
	v_readlane_b32 s2, v250, 17
	v_rcp_iflag_f32_e32 v149, v2
	v_readlane_b32 s3, v250, 18
	v_cvt_pk_bf16_f32 v147, v130, v131
	s_mov_b32 s58, 0x20000
	v_mul_f32_e32 v128, v148, v149
	v_trunc_f32_e32 v128, v128
	v_cvt_u32_f32_e32 v129, v128
	v_fma_f32 v128, -v128, v2, v148
	v_cmp_ge_f32_e64 s[20:21], |v128|, v2
	s_cmp_lg_u64 s[20:21], 0
	v_readfirstlane_b32 s11, v129
	s_addc_u32 s11, s11, 0
	s_and_b32 s11, s11, 0xff
	s_mul_hi_u32 s17, s11, 0x2800000
	s_mul_i32 s11, s11, 0x2800000
	s_add_u32 s20, s2, s11
	s_addc_u32 s21, s3, s17
	s_lshl_b32 s11, s50, 9
	s_lshl_b32 s17, s49, 20
	s_add_i32 s11, s11, s17
	v_add_u32_e32 v2, s11, v144
	v_lshl_add_u64 v[128:129], s[20:21], 0, v[2:3]
	s_mov_b32 s2, 0x10000
	v_cvt_pk_bf16_f32 v148, v124, v125
	v_cvt_pk_bf16_f32 v149, v126, v127
	global_store_dwordx4 v2, v[146:149], s[20:21]
	v_cvt_pk_bf16_f32 v116, v116, v117
	v_cvt_pk_bf16_f32 v117, v118, v119
	v_cvt_pk_bf16_f32 v118, v108, v109
	v_cvt_pk_bf16_f32 v119, v110, v111
	global_store_dwordx4 v2, v[116:119], s[20:21] offset:256
	v_cvt_pk_bf16_f32 v108, v120, v121
	v_cvt_pk_bf16_f32 v109, v122, v123
	v_cvt_pk_bf16_f32 v110, v112, v113
	v_add_co_u32_e32 v112, vcc, s2, v128
	v_cvt_pk_bf16_f32 v111, v114, v115
	s_mov_b32 s2, 0x30000
	s_nop 0
	v_addc_co_u32_e32 v113, vcc, 0, v129, vcc
	global_store_dwordx4 v[112:113], v[108:111], off
	v_cvt_pk_bf16_f32 v100, v100, v101
	v_cvt_pk_bf16_f32 v101, v102, v103
	v_cvt_pk_bf16_f32 v102, v92, v93
	v_cvt_pk_bf16_f32 v103, v94, v95
	global_store_dwordx4 v[112:113], v[100:103], off offset:256
	v_cvt_pk_bf16_f32 v92, v104, v105
	v_cvt_pk_bf16_f32 v93, v106, v107
	v_cvt_pk_bf16_f32 v94, v96, v97
	v_add_co_u32_e32 v96, vcc, s58, v128
	v_cvt_pk_bf16_f32 v95, v98, v99
	v_readlane_b32 s54, v250, 52
	s_nop 0
	v_addc_co_u32_e32 v97, vcc, 0, v129, vcc
	global_store_dwordx4 v[96:97], v[92:95], off
	v_cvt_pk_bf16_f32 v84, v84, v85
	v_cvt_pk_bf16_f32 v85, v86, v87
	v_cvt_pk_bf16_f32 v86, v76, v77
	v_cvt_pk_bf16_f32 v87, v78, v79
	global_store_dwordx4 v[96:97], v[84:87], off offset:256
	v_cvt_pk_bf16_f32 v76, v88, v89
	v_cvt_pk_bf16_f32 v77, v90, v91
	v_cvt_pk_bf16_f32 v78, v80, v81
	v_add_co_u32_e32 v80, vcc, s2, v128
	s_mov_b32 s2, 0x80000
	s_nop 0
	v_addc_co_u32_e32 v81, vcc, 0, v129, vcc
	v_cvt_pk_bf16_f32 v79, v82, v83
	global_store_dwordx4 v[80:81], v[76:79], off
	v_cvt_pk_bf16_f32 v72, v72, v73
	v_cvt_pk_bf16_f32 v73, v74, v75
	v_cvt_pk_bf16_f32 v74, v68, v69
	v_cvt_pk_bf16_f32 v75, v70, v71
	global_store_dwordx4 v[80:81], v[72:75], off offset:256
	v_cvt_pk_bf16_f32 v64, v64, v65
	v_cvt_pk_bf16_f32 v65, v66, v67
	v_cvt_pk_bf16_f32 v66, v60, v61
	v_add_co_u32_e32 v60, vcc, s2, v128
	s_mov_b32 s2, 0x90000
	s_nop 0
	v_addc_co_u32_e32 v61, vcc, 0, v129, vcc
	v_cvt_pk_bf16_f32 v67, v62, v63
	global_store_dwordx4 v[60:61], v[64:67], off
	v_cvt_pk_bf16_f32 v52, v52, v53
	v_cvt_pk_bf16_f32 v53, v54, v55
	v_cvt_pk_bf16_f32 v54, v44, v45
	v_cvt_pk_bf16_f32 v55, v46, v47
	global_store_dwordx4 v[60:61], v[52:55], off offset:256
	v_cvt_pk_bf16_f32 v44, v56, v57
	v_cvt_pk_bf16_f32 v45, v58, v59
	v_cvt_pk_bf16_f32 v46, v48, v49
	v_add_co_u32_e32 v48, vcc, s2, v128
	s_mov_b32 s2, 0xa0000
	s_nop 0
	v_addc_co_u32_e32 v49, vcc, 0, v129, vcc
	v_cvt_pk_bf16_f32 v47, v50, v51
	global_store_dwordx4 v[48:49], v[44:47], off
	v_cvt_pk_bf16_f32 v36, v36, v37
	v_cvt_pk_bf16_f32 v37, v38, v39
	v_cvt_pk_bf16_f32 v38, v28, v29
	v_cvt_pk_bf16_f32 v39, v30, v31
	global_store_dwordx4 v[48:49], v[36:39], off offset:256
	v_cvt_pk_bf16_f32 v28, v40, v41
	v_cvt_pk_bf16_f32 v29, v42, v43
	v_cvt_pk_bf16_f32 v30, v32, v33
	v_add_co_u32_e32 v32, vcc, s2, v128
	s_mov_b32 s2, 0xb0000
	s_nop 0
	v_addc_co_u32_e32 v33, vcc, 0, v129, vcc
	v_cvt_pk_bf16_f32 v31, v34, v35
	global_store_dwordx4 v[32:33], v[28:31], off
	v_cvt_pk_bf16_f32 v20, v20, v21
	v_cvt_pk_bf16_f32 v21, v22, v23
	v_cvt_pk_bf16_f32 v22, v12, v13
	v_cvt_pk_bf16_f32 v23, v14, v15
	global_store_dwordx4 v[32:33], v[20:23], off offset:256
	v_cvt_pk_bf16_f32 v12, v24, v25
	v_cvt_pk_bf16_f32 v13, v26, v27
	v_cvt_pk_bf16_f32 v14, v16, v17
	v_add_co_u32_e32 v16, vcc, s2, v128
	s_mov_b64 s[20:21], -1
	s_nop 0
	v_addc_co_u32_e32 v17, vcc, 0, v129, vcc
	s_and_b64 vcc, exec, s[36:37]
	s_mov_b64 s[56:57], 0x40000
	v_readlane_b32 s55, v250, 53
	v_cvt_pk_bf16_f32 v15, v18, v19
	global_store_dwordx4 v[16:17], v[12:15], off
	v_cvt_pk_bf16_f32 v8, v8, v9
	v_cvt_pk_bf16_f32 v9, v10, v11
	v_cvt_pk_bf16_f32 v10, v4, v5
	v_cvt_pk_bf16_f32 v11, v6, v7
	global_store_dwordx4 v[16:17], v[8:11], off offset:256
.Ljoin_ff2:
	s_cbranch_vccnz .LBB0_1287
	s_and_b64 s[14:15], s[14:15], exec
	s_cselect_b32 s51, 32, s47
	s_andn2_b64 vcc, exec, s[6:7]
	s_cbranch_vccnz .LBB0_1286
	s_barrier
	s_branch .LBB0_1286
.Llast_ff2:
	v_cvt_f32_u32_e32 v2, s51
	v_cvt_f32_u32_e32 v148, s52
	v_cvt_pk_bf16_f32 v146, v128, v129
	v_readlane_b32 s2, v250, 17
	v_rcp_iflag_f32_e32 v149, v2
	v_readlane_b32 s3, v250, 18
	v_cvt_pk_bf16_f32 v147, v130, v131
	s_mov_b32 s58, 0x20000
	v_mul_f32_e32 v128, v148, v149
	v_trunc_f32_e32 v128, v128
	v_cvt_u32_f32_e32 v129, v128
	v_fma_f32 v128, -v128, v2, v148
	v_cmp_ge_f32_e64 s[20:21], |v128|, v2
	s_cmp_lg_u64 s[20:21], 0
	v_readfirstlane_b32 s11, v129
	s_addc_u32 s11, s11, 0
	s_and_b32 s11, s11, 0xff
	s_mul_hi_u32 s17, s11, 0x2800000
	s_mul_i32 s11, s11, 0x2800000
	s_add_u32 s20, s2, s11
	s_addc_u32 s21, s3, s17
	s_lshl_b32 s11, s50, 9
	s_lshl_b32 s17, s49, 20
	s_add_i32 s11, s11, s17
	v_add_u32_e32 v2, s11, v144
	v_lshl_add_u64 v[128:129], s[20:21], 0, v[2:3]
	s_mov_b32 s2, 0x10000
	v_cvt_pk_bf16_f32 v148, v124, v125
	v_cvt_pk_bf16_f32 v149, v126, v127
	global_store_dwordx4 v2, v[146:149], s[20:21] sc0 sc1
	v_cvt_pk_bf16_f32 v116, v116, v117
	v_cvt_pk_bf16_f32 v117, v118, v119
	v_cvt_pk_bf16_f32 v118, v108, v109
	v_cvt_pk_bf16_f32 v119, v110, v111
	global_store_dwordx4 v2, v[116:119], s[20:21] offset:256 sc0 sc1
	v_cvt_pk_bf16_f32 v108, v120, v121
	v_cvt_pk_bf16_f32 v109, v122, v123
	v_cvt_pk_bf16_f32 v110, v112, v113
	v_add_co_u32_e32 v112, vcc, s2, v128
	v_cvt_pk_bf16_f32 v111, v114, v115
	s_mov_b32 s2, 0x30000
	s_nop 0
	v_addc_co_u32_e32 v113, vcc, 0, v129, vcc
	global_store_dwordx4 v[112:113], v[108:111], off sc0 sc1
	v_cvt_pk_bf16_f32 v100, v100, v101
	v_cvt_pk_bf16_f32 v101, v102, v103
	v_cvt_pk_bf16_f32 v102, v92, v93
	v_cvt_pk_bf16_f32 v103, v94, v95
	global_store_dwordx4 v[112:113], v[100:103], off offset:256 sc0 sc1
	v_cvt_pk_bf16_f32 v92, v104, v105
	v_cvt_pk_bf16_f32 v93, v106, v107
	v_cvt_pk_bf16_f32 v94, v96, v97
	v_add_co_u32_e32 v96, vcc, s58, v128
	v_cvt_pk_bf16_f32 v95, v98, v99
	v_readlane_b32 s54, v250, 52
	s_nop 0
	v_addc_co_u32_e32 v97, vcc, 0, v129, vcc
	global_store_dwordx4 v[96:97], v[92:95], off sc0 sc1
	v_cvt_pk_bf16_f32 v84, v84, v85
	v_cvt_pk_bf16_f32 v85, v86, v87
	v_cvt_pk_bf16_f32 v86, v76, v77
	v_cvt_pk_bf16_f32 v87, v78, v79
	global_store_dwordx4 v[96:97], v[84:87], off offset:256 sc0 sc1
	v_cvt_pk_bf16_f32 v76, v88, v89
	v_cvt_pk_bf16_f32 v77, v90, v91
	v_cvt_pk_bf16_f32 v78, v80, v81
	v_add_co_u32_e32 v80, vcc, s2, v128
	s_mov_b32 s2, 0x80000
	s_nop 0
	v_addc_co_u32_e32 v81, vcc, 0, v129, vcc
	v_cvt_pk_bf16_f32 v79, v82, v83
	global_store_dwordx4 v[80:81], v[76:79], off sc0 sc1
	v_cvt_pk_bf16_f32 v72, v72, v73
	v_cvt_pk_bf16_f32 v73, v74, v75
	v_cvt_pk_bf16_f32 v74, v68, v69
	v_cvt_pk_bf16_f32 v75, v70, v71
	global_store_dwordx4 v[80:81], v[72:75], off offset:256 sc0 sc1
	v_cvt_pk_bf16_f32 v64, v64, v65
	v_cvt_pk_bf16_f32 v65, v66, v67
	v_cvt_pk_bf16_f32 v66, v60, v61
	v_add_co_u32_e32 v60, vcc, s2, v128
	s_mov_b32 s2, 0x90000
	s_nop 0
	v_addc_co_u32_e32 v61, vcc, 0, v129, vcc
	v_cvt_pk_bf16_f32 v67, v62, v63
	global_store_dwordx4 v[60:61], v[64:67], off sc0 sc1
	v_cvt_pk_bf16_f32 v52, v52, v53
	v_cvt_pk_bf16_f32 v53, v54, v55
	v_cvt_pk_bf16_f32 v54, v44, v45
	v_cvt_pk_bf16_f32 v55, v46, v47
	global_store_dwordx4 v[60:61], v[52:55], off offset:256 sc0 sc1
	v_cvt_pk_bf16_f32 v44, v56, v57
	v_cvt_pk_bf16_f32 v45, v58, v59
	v_cvt_pk_bf16_f32 v46, v48, v49
	v_add_co_u32_e32 v48, vcc, s2, v128
	s_mov_b32 s2, 0xa0000
	s_nop 0
	v_addc_co_u32_e32 v49, vcc, 0, v129, vcc
	v_cvt_pk_bf16_f32 v47, v50, v51
	global_store_dwordx4 v[48:49], v[44:47], off sc0 sc1
	v_cvt_pk_bf16_f32 v36, v36, v37
	v_cvt_pk_bf16_f32 v37, v38, v39
	v_cvt_pk_bf16_f32 v38, v28, v29
	v_cvt_pk_bf16_f32 v39, v30, v31
	global_store_dwordx4 v[48:49], v[36:39], off offset:256 sc0 sc1
	v_cvt_pk_bf16_f32 v28, v40, v41
	v_cvt_pk_bf16_f32 v29, v42, v43
	v_cvt_pk_bf16_f32 v30, v32, v33
	v_add_co_u32_e32 v32, vcc, s2, v128
	s_mov_b32 s2, 0xb0000
	s_nop 0
	v_addc_co_u32_e32 v33, vcc, 0, v129, vcc
	v_cvt_pk_bf16_f32 v31, v34, v35
	global_store_dwordx4 v[32:33], v[28:31], off sc0 sc1
	v_cvt_pk_bf16_f32 v20, v20, v21
	v_cvt_pk_bf16_f32 v21, v22, v23
	v_cvt_pk_bf16_f32 v22, v12, v13
	v_cvt_pk_bf16_f32 v23, v14, v15
	global_store_dwordx4 v[32:33], v[20:23], off offset:256 sc0 sc1
	v_cvt_pk_bf16_f32 v12, v24, v25
	v_cvt_pk_bf16_f32 v13, v26, v27
	v_cvt_pk_bf16_f32 v14, v16, v17
	v_add_co_u32_e32 v16, vcc, s2, v128
	s_mov_b64 s[20:21], -1
	s_nop 0
	v_addc_co_u32_e32 v17, vcc, 0, v129, vcc
	s_and_b64 vcc, exec, s[36:37]
	s_mov_b64 s[56:57], 0x40000
	v_readlane_b32 s55, v250, 53
	v_cvt_pk_bf16_f32 v15, v18, v19
	global_store_dwordx4 v[16:17], v[12:15], off sc0 sc1
	v_cvt_pk_bf16_f32 v8, v8, v9
	v_cvt_pk_bf16_f32 v9, v10, v11
	v_cvt_pk_bf16_f32 v10, v4, v5
	v_cvt_pk_bf16_f32 v11, v6, v7
	global_store_dwordx4 v[16:17], v[8:11], off offset:256 sc0 sc1
	s_branch .Ljoin_ff2
